# LDS-DMA for stage n+2 issued right after the first fragment reads, no s_setprio in the rolled K-loops, MLA row max as v_max3 chains
# baseline (speedup 1.0000x reference)
; #define BLOAD(A_, B_, kt) do { _Pragma("unroll") for (int i = 0; i < 4; ++i) { \
;     A_[i] = *(const u32x4*)((const char*)Ap + (aoff + (unsigned)(32 * i * lda + (kt) * 64) * 2u)); B_[i] = *(const u32x4*)((const char*)Wt + (woff + (unsigned)(32 * i * K + (kt) * 64) * 2u)); } } while (0)
; #define BLOAD(A_, B_, kt) do { _Pragma("unroll") for (int i = 0; i < 4; ++i) { \
;     A_[i] = *(const u32x4*)((const char*)Ap + (aoff + (unsigned)(32 * i * lda + (kt) * 64) * 2u)); B_[i] = *(const u32x4*)((const char*)Wt + (woff + (unsigned)(32 * i * K + (kt) * 64) * 2u)); } } while (0)
; #define BSTORE(A_, B_, buf) do { _Pragma("unroll") for (int i = 0; i < 4; ++i) { \
;     *(u32x4*)&As[(buf) * GBUF + (srow + 32 * i) * LDT + sc8] = A_[i]; \
;     *(u32x4*)&Bs[(buf) * GBUF + (srow + 32 * i) * LDT + sc8] = B_[i]; } } while (0)
; template <int NK>
; DI void gemm_run(PF& pf, const u16* __restrict__ Ap, int lda, const u16* __restrict__ Wt, f32x16 (&acc)[2][2], char* smem) {
;     ...
;   __builtin_amdgcn_s_setprio(0);
;   __syncthreads();
;   BSTORE(pf.a0, pf.b0, 0);
;   BLOAD(pf.a0, pf.b0, 2);
;   __syncthreads();
; #pragma unroll
;   for (int kt = 0; kt < nk; kt += 2) {
;     BCOMP(0);
;     BSTORE(pf.a1, pf.b1, 1);
;     if (kt + 3 < nk) BLOAD(pf.a1, pf.b1, kt + 3);
;     __syncthreads();
;     BCOMP(1);
;     if (kt + 2 < nk) { BSTORE(pf.a0, pf.b0, 0); if (kt + 4 < nk) BLOAD(pf.a0, pf.b0, kt + 4); }
;     __syncthreads();
;   }
.Lffn2_kloop:
	s_waitcnt vmcnt(6)
	s_barrier
	ds_read_b128 v[224:227], v126 offset:0
	ds_read_b128 v[240:243], v128 offset:0
	ds_read_b128 v[244:247], v128 offset:1024
	ds_read_b128 v[248:251], v128 offset:2048
	ds_read_b128 v[156:159], v128 offset:3072
	s_add_u32 m0, s16, 0xc000
	s_add_u32 s42, s42, 0x100000
	s_addc_u32 s43, s43, 0
	global_load_lds_dwordx4 v137, s[42:43]
	global_load_lds_dwordx4 v150, s[42:43] offset:1024
	s_add_u32 m0, s0, 0xc000
	s_add_u32 s30, s30, 0x10000
	s_addc_u32 s31, s31, 0
	global_load_lds_dwordx4 v151, s[30:31]
	global_load_lds_dwordx4 v152, s[30:31] offset:1024
	global_load_lds_dwordx4 v153, s[30:31] offset:2048
	global_load_lds_dwordx4 v154, s[30:31] offset:3072
	ds_read_b128 v[228:231], v126 offset:1024
	ds_read_b128 v[232:235], v126 offset:2048
	ds_read_b128 v[236:239], v126 offset:3072
	ds_read_b128 v[160:163], v128 offset:8192
	ds_read_b128 v[164:167], v128 offset:9216
	ds_read_b128 v[168:171], v128 offset:10240
	ds_read_b128 v[122:125], v128 offset:11264
	s_waitcnt lgkmcnt(10)
	v_mfma_f32_16x16x32_bf16 v[2:5], v[224:227], v[240:243], v[2:5]
	s_waitcnt lgkmcnt(9)
	v_mfma_f32_16x16x32_bf16 v[6:9], v[224:227], v[244:247], v[6:9]
	s_waitcnt lgkmcnt(8)
	v_mfma_f32_16x16x32_bf16 v[10:13], v[224:227], v[248:251], v[10:13]
	s_waitcnt lgkmcnt(7)
	v_mfma_f32_16x16x32_bf16 v[14:17], v[224:227], v[156:159], v[14:17]
	s_waitcnt lgkmcnt(6)
	v_mfma_f32_16x16x32_bf16 v[18:21], v[228:231], v[240:243], v[18:21]
	v_mfma_f32_16x16x32_bf16 v[22:25], v[228:231], v[244:247], v[22:25]
	v_mfma_f32_16x16x32_bf16 v[26:29], v[228:231], v[248:251], v[26:29]
	v_mfma_f32_16x16x32_bf16 v[30:33], v[228:231], v[156:159], v[30:33]
	s_waitcnt lgkmcnt(5)
	v_mfma_f32_16x16x32_bf16 v[34:37], v[232:235], v[240:243], v[34:37]
	v_mfma_f32_16x16x32_bf16 v[38:41], v[232:235], v[244:247], v[38:41]
	v_mfma_f32_16x16x32_bf16 v[42:45], v[232:235], v[248:251], v[42:45]
	v_mfma_f32_16x16x32_bf16 v[46:49], v[232:235], v[156:159], v[46:49]
	s_waitcnt lgkmcnt(4)
	v_mfma_f32_16x16x32_bf16 v[50:53], v[236:239], v[240:243], v[50:53]
	v_mfma_f32_16x16x32_bf16 v[54:57], v[236:239], v[244:247], v[54:57]
	v_mfma_f32_16x16x32_bf16 v[58:61], v[236:239], v[248:251], v[58:61]
	v_mfma_f32_16x16x32_bf16 v[62:65], v[236:239], v[156:159], v[62:65]
	s_waitcnt lgkmcnt(3)
	v_mfma_f32_16x16x32_bf16 v[74:77], v[224:227], v[160:163], v[74:77]
	s_waitcnt lgkmcnt(2)
	v_mfma_f32_16x16x32_bf16 v[78:81], v[224:227], v[164:167], v[78:81]
	s_waitcnt lgkmcnt(1)
	v_mfma_f32_16x16x32_bf16 v[82:85], v[224:227], v[168:171], v[82:85]
	s_waitcnt lgkmcnt(0)
	v_mfma_f32_16x16x32_bf16 v[86:89], v[224:227], v[122:125], v[86:89]
	v_mfma_f32_16x16x32_bf16 v[90:93], v[228:231], v[160:163], v[90:93]
	v_mfma_f32_16x16x32_bf16 v[94:97], v[228:231], v[164:167], v[94:97]
	v_mfma_f32_16x16x32_bf16 v[98:101], v[228:231], v[168:171], v[98:101]
	v_mfma_f32_16x16x32_bf16 v[102:105], v[228:231], v[122:125], v[102:105]
	v_mfma_f32_16x16x32_bf16 v[106:109], v[232:235], v[160:163], v[106:109]
	v_mfma_f32_16x16x32_bf16 v[110:113], v[232:235], v[164:167], v[110:113]
	v_mfma_f32_16x16x32_bf16 v[114:117], v[232:235], v[168:171], v[114:117]
	v_mfma_f32_16x16x32_bf16 v[118:121], v[232:235], v[122:125], v[118:121]
	v_mfma_f32_16x16x32_bf16 v[208:211], v[236:239], v[160:163], v[208:211]
	v_mfma_f32_16x16x32_bf16 v[212:215], v[236:239], v[164:167], v[212:215]
	v_mfma_f32_16x16x32_bf16 v[216:219], v[236:239], v[168:171], v[216:219]
	v_mfma_f32_16x16x32_bf16 v[220:223], v[236:239], v[122:125], v[220:223]
	s_waitcnt vmcnt(6)
	s_barrier
	ds_read_b128 v[224:227], v126 offset:24576
	ds_read_b128 v[240:243], v128 offset:24576
	ds_read_b128 v[244:247], v128 offset:25600
	ds_read_b128 v[248:251], v128 offset:26624
	ds_read_b128 v[156:159], v128 offset:27648
	s_add_u32 m0, s16, 0x0
	s_add_u32 s42, s42, 0x100000
	s_addc_u32 s43, s43, 0
	global_load_lds_dwordx4 v137, s[42:43]
	global_load_lds_dwordx4 v150, s[42:43] offset:1024
	s_add_u32 m0, s0, 0x0
	s_add_u32 s30, s30, 0x10000
	s_addc_u32 s31, s31, 0
	global_load_lds_dwordx4 v151, s[30:31]
	global_load_lds_dwordx4 v152, s[30:31] offset:1024
	global_load_lds_dwordx4 v153, s[30:31] offset:2048
	global_load_lds_dwordx4 v154, s[30:31] offset:3072
	ds_read_b128 v[228:231], v126 offset:25600
	ds_read_b128 v[232:235], v126 offset:26624
	ds_read_b128 v[236:239], v126 offset:27648
	ds_read_b128 v[160:163], v128 offset:32768
	ds_read_b128 v[164:167], v128 offset:33792
	ds_read_b128 v[168:171], v128 offset:34816
	ds_read_b128 v[122:125], v128 offset:35840
	s_waitcnt lgkmcnt(10)
	v_mfma_f32_16x16x32_bf16 v[2:5], v[224:227], v[240:243], v[2:5]
	s_waitcnt lgkmcnt(9)
	v_mfma_f32_16x16x32_bf16 v[6:9], v[224:227], v[244:247], v[6:9]
	s_waitcnt lgkmcnt(8)
	v_mfma_f32_16x16x32_bf16 v[10:13], v[224:227], v[248:251], v[10:13]
	s_waitcnt lgkmcnt(7)
	v_mfma_f32_16x16x32_bf16 v[14:17], v[224:227], v[156:159], v[14:17]
	s_waitcnt lgkmcnt(6)
	v_mfma_f32_16x16x32_bf16 v[18:21], v[228:231], v[240:243], v[18:21]
	v_mfma_f32_16x16x32_bf16 v[22:25], v[228:231], v[244:247], v[22:25]
	v_mfma_f32_16x16x32_bf16 v[26:29], v[228:231], v[248:251], v[26:29]
	v_mfma_f32_16x16x32_bf16 v[30:33], v[228:231], v[156:159], v[30:33]
	s_waitcnt lgkmcnt(5)
	v_mfma_f32_16x16x32_bf16 v[34:37], v[232:235], v[240:243], v[34:37]
	v_mfma_f32_16x16x32_bf16 v[38:41], v[232:235], v[244:247], v[38:41]
	v_mfma_f32_16x16x32_bf16 v[42:45], v[232:235], v[248:251], v[42:45]
	v_mfma_f32_16x16x32_bf16 v[46:49], v[232:235], v[156:159], v[46:49]
	s_waitcnt lgkmcnt(4)
	v_mfma_f32_16x16x32_bf16 v[50:53], v[236:239], v[240:243], v[50:53]
	v_mfma_f32_16x16x32_bf16 v[54:57], v[236:239], v[244:247], v[54:57]
	v_mfma_f32_16x16x32_bf16 v[58:61], v[236:239], v[248:251], v[58:61]
	v_mfma_f32_16x16x32_bf16 v[62:65], v[236:239], v[156:159], v[62:65]
	s_waitcnt lgkmcnt(3)
	v_mfma_f32_16x16x32_bf16 v[74:77], v[224:227], v[160:163], v[74:77]
	s_waitcnt lgkmcnt(2)
	v_mfma_f32_16x16x32_bf16 v[78:81], v[224:227], v[164:167], v[78:81]
	s_waitcnt lgkmcnt(1)
	v_mfma_f32_16x16x32_bf16 v[82:85], v[224:227], v[168:171], v[82:85]
	s_waitcnt lgkmcnt(0)
	v_mfma_f32_16x16x32_bf16 v[86:89], v[224:227], v[122:125], v[86:89]
	v_mfma_f32_16x16x32_bf16 v[90:93], v[228:231], v[160:163], v[90:93]
	v_mfma_f32_16x16x32_bf16 v[94:97], v[228:231], v[164:167], v[94:97]
	v_mfma_f32_16x16x32_bf16 v[98:101], v[228:231], v[168:171], v[98:101]
	v_mfma_f32_16x16x32_bf16 v[102:105], v[228:231], v[122:125], v[102:105]
	v_mfma_f32_16x16x32_bf16 v[106:109], v[232:235], v[160:163], v[106:109]
	v_mfma_f32_16x16x32_bf16 v[110:113], v[232:235], v[164:167], v[110:113]
	v_mfma_f32_16x16x32_bf16 v[114:117], v[232:235], v[168:171], v[114:117]
	v_mfma_f32_16x16x32_bf16 v[118:121], v[232:235], v[122:125], v[118:121]
	v_mfma_f32_16x16x32_bf16 v[208:211], v[236:239], v[160:163], v[208:211]
	v_mfma_f32_16x16x32_bf16 v[212:215], v[236:239], v[164:167], v[212:215]
	v_mfma_f32_16x16x32_bf16 v[216:219], v[236:239], v[168:171], v[216:219]
	v_mfma_f32_16x16x32_bf16 v[220:223], v[236:239], v[122:125], v[220:223]
	s_waitcnt vmcnt(6)
	s_barrier
; #define BLOAD(A_, B_, kt) do { _Pragma("unroll") for (int i = 0; i < 4; ++i) { \
;     A_[i] = *(const u32x4*)((const char*)Ap + (aoff + (unsigned)(32 * i * lda + (kt) * 64) * 2u)); B_[i] = *(const u32x4*)((const char*)Wt + (woff + (unsigned)(32 * i * K + (kt) * 64) * 2u)); } } while (0)
; #define BLOAD(A_, B_, kt) do { _Pragma("unroll") for (int i = 0; i < 4; ++i) { \
;     A_[i] = *(const u32x4*)((const char*)Ap + (aoff + (unsigned)(32 * i * lda + (kt) * 64) * 2u)); B_[i] = *(const u32x4*)((const char*)Wt + (woff + (unsigned)(32 * i * K + (kt) * 64) * 2u)); } } while (0)
; #define BSTORE(A_, B_, buf) do { _Pragma("unroll") for (int i = 0; i < 4; ++i) { \
;     *(u32x4*)&As[(buf) * GBUF + (srow + 32 * i) * LDT + sc8] = A_[i]; \
;     *(u32x4*)&Bs[(buf) * GBUF + (srow + 32 * i) * LDT + sc8] = B_[i]; } } while (0)
; template <int NK>
; DI void gemm_run(PF& pf, const u16* __restrict__ Ap, int lda, const u16* __restrict__ Wt, f32x16 (&acc)[2][2], char* smem) {
;     ...
;   __builtin_amdgcn_s_setprio(0);
;   __syncthreads();
;   BSTORE(pf.a0, pf.b0, 0);
;   BLOAD(pf.a0, pf.b0, 2);
;   __syncthreads();
; #pragma unroll
;   for (int kt = 0; kt < nk; kt += 2) {
;     BCOMP(0);
;     BSTORE(pf.a1, pf.b1, 1);
;     if (kt + 3 < nk) BLOAD(pf.a1, pf.b1, kt + 3);
;     __syncthreads();
;     BCOMP(1);
;     if (kt + 2 < nk) { BSTORE(pf.a0, pf.b0, 0); if (kt + 4 < nk) BLOAD(pf.a0, pf.b0, kt + 4); }
;     __syncthreads();
;   }
	ds_read_b128 v[224:227], v126 offset:49152
	ds_read_b128 v[240:243], v128 offset:49152
	ds_read_b128 v[244:247], v128 offset:50176
	ds_read_b128 v[248:251], v128 offset:51200
	ds_read_b128 v[156:159], v128 offset:52224
	s_add_u32 m0, s16, 0x6000
	s_add_u32 s42, s42, 0x100000
	s_addc_u32 s43, s43, 0
	global_load_lds_dwordx4 v137, s[42:43]
	global_load_lds_dwordx4 v150, s[42:43] offset:1024
	s_add_u32 m0, s0, 0x6000
	s_add_u32 s30, s30, 0x10000
	s_addc_u32 s31, s31, 0
	global_load_lds_dwordx4 v151, s[30:31]
	global_load_lds_dwordx4 v152, s[30:31] offset:1024
	global_load_lds_dwordx4 v153, s[30:31] offset:2048
	global_load_lds_dwordx4 v154, s[30:31] offset:3072
	ds_read_b128 v[228:231], v126 offset:50176
	ds_read_b128 v[232:235], v126 offset:51200
	ds_read_b128 v[236:239], v126 offset:52224
	ds_read_b128 v[160:163], v128 offset:57344
	ds_read_b128 v[164:167], v128 offset:58368
	ds_read_b128 v[168:171], v128 offset:59392
	ds_read_b128 v[122:125], v128 offset:60416
	s_waitcnt lgkmcnt(10)
	v_mfma_f32_16x16x32_bf16 v[2:5], v[224:227], v[240:243], v[2:5]
	s_waitcnt lgkmcnt(9)
	v_mfma_f32_16x16x32_bf16 v[6:9], v[224:227], v[244:247], v[6:9]
	s_waitcnt lgkmcnt(8)
	v_mfma_f32_16x16x32_bf16 v[10:13], v[224:227], v[248:251], v[10:13]
	s_waitcnt lgkmcnt(7)
	v_mfma_f32_16x16x32_bf16 v[14:17], v[224:227], v[156:159], v[14:17]
	s_waitcnt lgkmcnt(6)
	v_mfma_f32_16x16x32_bf16 v[18:21], v[228:231], v[240:243], v[18:21]
	v_mfma_f32_16x16x32_bf16 v[22:25], v[228:231], v[244:247], v[22:25]
	v_mfma_f32_16x16x32_bf16 v[26:29], v[228:231], v[248:251], v[26:29]
	v_mfma_f32_16x16x32_bf16 v[30:33], v[228:231], v[156:159], v[30:33]
	s_waitcnt lgkmcnt(5)
	v_mfma_f32_16x16x32_bf16 v[34:37], v[232:235], v[240:243], v[34:37]
	v_mfma_f32_16x16x32_bf16 v[38:41], v[232:235], v[244:247], v[38:41]
	v_mfma_f32_16x16x32_bf16 v[42:45], v[232:235], v[248:251], v[42:45]
	v_mfma_f32_16x16x32_bf16 v[46:49], v[232:235], v[156:159], v[46:49]
	s_waitcnt lgkmcnt(4)
	v_mfma_f32_16x16x32_bf16 v[50:53], v[236:239], v[240:243], v[50:53]
	v_mfma_f32_16x16x32_bf16 v[54:57], v[236:239], v[244:247], v[54:57]
	v_mfma_f32_16x16x32_bf16 v[58:61], v[236:239], v[248:251], v[58:61]
	v_mfma_f32_16x16x32_bf16 v[62:65], v[236:239], v[156:159], v[62:65]
	s_waitcnt lgkmcnt(3)
	v_mfma_f32_16x16x32_bf16 v[74:77], v[224:227], v[160:163], v[74:77]
	s_waitcnt lgkmcnt(2)
	v_mfma_f32_16x16x32_bf16 v[78:81], v[224:227], v[164:167], v[78:81]
	s_waitcnt lgkmcnt(1)
	v_mfma_f32_16x16x32_bf16 v[82:85], v[224:227], v[168:171], v[82:85]
	s_waitcnt lgkmcnt(0)
	v_mfma_f32_16x16x32_bf16 v[86:89], v[224:227], v[122:125], v[86:89]
	v_mfma_f32_16x16x32_bf16 v[90:93], v[228:231], v[160:163], v[90:93]
	v_mfma_f32_16x16x32_bf16 v[94:97], v[228:231], v[164:167], v[94:97]
	v_mfma_f32_16x16x32_bf16 v[98:101], v[228:231], v[168:171], v[98:101]
	v_mfma_f32_16x16x32_bf16 v[102:105], v[228:231], v[122:125], v[102:105]
	v_mfma_f32_16x16x32_bf16 v[106:109], v[232:235], v[160:163], v[106:109]
	v_mfma_f32_16x16x32_bf16 v[110:113], v[232:235], v[164:167], v[110:113]
	v_mfma_f32_16x16x32_bf16 v[114:117], v[232:235], v[168:171], v[114:117]
	v_mfma_f32_16x16x32_bf16 v[118:121], v[232:235], v[122:125], v[118:121]
	v_mfma_f32_16x16x32_bf16 v[208:211], v[236:239], v[160:163], v[208:211]
	v_mfma_f32_16x16x32_bf16 v[212:215], v[236:239], v[164:167], v[212:215]
	v_mfma_f32_16x16x32_bf16 v[216:219], v[236:239], v[168:171], v[216:219]
	v_mfma_f32_16x16x32_bf16 v[220:223], v[236:239], v[122:125], v[220:223]
	s_sub_u32 s46, s46, 1
	s_cmp_lg_u32 s46, 0
	s_cbranch_scc1 .Lffn2_kloop
	s_waitcnt vmcnt(6)
	s_barrier
; #define BLOAD(A_, B_, kt) do { _Pragma("unroll") for (int i = 0; i < 4; ++i) { \
;     A_[i] = *(const u32x4*)((const char*)Ap + (aoff + (unsigned)(32 * i * lda + (kt) * 64) * 2u)); B_[i] = *(const u32x4*)((const char*)Wt + (woff + (unsigned)(32 * i * K + (kt) * 64) * 2u)); } } while (0)
; #define BLOAD(A_, B_, kt) do { _Pragma("unroll") for (int i = 0; i < 4; ++i) { \
;     A_[i] = *(const u32x4*)((const char*)Ap + (aoff + (unsigned)(32 * i * lda + (kt) * 64) * 2u)); B_[i] = *(const u32x4*)((const char*)Wt + (woff + (unsigned)(32 * i * K + (kt) * 64) * 2u)); } } while (0)
; #define BSTORE(A_, B_, buf) do { _Pragma("unroll") for (int i = 0; i < 4; ++i) { \
;     *(u32x4*)&As[(buf) * GBUF + (srow + 32 * i) * LDT + sc8] = A_[i]; \
;     *(u32x4*)&Bs[(buf) * GBUF + (srow + 32 * i) * LDT + sc8] = B_[i]; } } while (0)
; template <int NK>
; DI void gemm_run(PF& pf, const u16* __restrict__ Ap, int lda, const u16* __restrict__ Wt, f32x16 (&acc)[2][2], char* smem) {
;     ...
;   __builtin_amdgcn_s_setprio(0);
;   __syncthreads();
;   BSTORE(pf.a0, pf.b0, 0);
;   BLOAD(pf.a0, pf.b0, 2);
;   __syncthreads();
; #pragma unroll
;   for (int kt = 0; kt < nk; kt += 2) {
;     BCOMP(0);
;     BSTORE(pf.a1, pf.b1, 1);
;     if (kt + 3 < nk) BLOAD(pf.a1, pf.b1, kt + 3);
;     __syncthreads();
;     BCOMP(1);
;     if (kt + 2 < nk) { BSTORE(pf.a0, pf.b0, 0); if (kt + 4 < nk) BLOAD(pf.a0, pf.b0, kt + 4); }
;     __syncthreads();
;   }
	ds_read_b128 v[224:227], v126 offset:0
	ds_read_b128 v[240:243], v128 offset:0
	ds_read_b128 v[244:247], v128 offset:1024
	ds_read_b128 v[248:251], v128 offset:2048
	ds_read_b128 v[156:159], v128 offset:3072
	ds_read_b128 v[228:231], v126 offset:1024
	ds_read_b128 v[232:235], v126 offset:2048
	ds_read_b128 v[236:239], v126 offset:3072
	ds_read_b128 v[160:163], v128 offset:8192
	ds_read_b128 v[164:167], v128 offset:9216
	ds_read_b128 v[168:171], v128 offset:10240
	ds_read_b128 v[122:125], v128 offset:11264
	s_waitcnt lgkmcnt(10)
	v_mfma_f32_16x16x32_bf16 v[2:5], v[224:227], v[240:243], v[2:5]
	s_waitcnt lgkmcnt(9)
	v_mfma_f32_16x16x32_bf16 v[6:9], v[224:227], v[244:247], v[6:9]
	s_waitcnt lgkmcnt(8)
	v_mfma_f32_16x16x32_bf16 v[10:13], v[224:227], v[248:251], v[10:13]
	s_waitcnt lgkmcnt(7)
	v_mfma_f32_16x16x32_bf16 v[14:17], v[224:227], v[156:159], v[14:17]
	s_waitcnt lgkmcnt(6)
	v_mfma_f32_16x16x32_bf16 v[18:21], v[228:231], v[240:243], v[18:21]
	v_mfma_f32_16x16x32_bf16 v[22:25], v[228:231], v[244:247], v[22:25]
	v_mfma_f32_16x16x32_bf16 v[26:29], v[228:231], v[248:251], v[26:29]
	v_mfma_f32_16x16x32_bf16 v[30:33], v[228:231], v[156:159], v[30:33]
	s_waitcnt lgkmcnt(5)
	v_mfma_f32_16x16x32_bf16 v[34:37], v[232:235], v[240:243], v[34:37]
	v_mfma_f32_16x16x32_bf16 v[38:41], v[232:235], v[244:247], v[38:41]
	v_mfma_f32_16x16x32_bf16 v[42:45], v[232:235], v[248:251], v[42:45]
	v_mfma_f32_16x16x32_bf16 v[46:49], v[232:235], v[156:159], v[46:49]
	s_waitcnt lgkmcnt(4)
	v_mfma_f32_16x16x32_bf16 v[50:53], v[236:239], v[240:243], v[50:53]
	v_mfma_f32_16x16x32_bf16 v[54:57], v[236:239], v[244:247], v[54:57]
	v_mfma_f32_16x16x32_bf16 v[58:61], v[236:239], v[248:251], v[58:61]
	v_mfma_f32_16x16x32_bf16 v[62:65], v[236:239], v[156:159], v[62:65]
	s_waitcnt lgkmcnt(3)
	v_mfma_f32_16x16x32_bf16 v[74:77], v[224:227], v[160:163], v[74:77]
	s_waitcnt lgkmcnt(2)
	v_mfma_f32_16x16x32_bf16 v[78:81], v[224:227], v[164:167], v[78:81]
	s_waitcnt lgkmcnt(1)
	v_mfma_f32_16x16x32_bf16 v[82:85], v[224:227], v[168:171], v[82:85]
	s_waitcnt lgkmcnt(0)
	v_mfma_f32_16x16x32_bf16 v[86:89], v[224:227], v[122:125], v[86:89]
	v_mfma_f32_16x16x32_bf16 v[90:93], v[228:231], v[160:163], v[90:93]
	v_mfma_f32_16x16x32_bf16 v[94:97], v[228:231], v[164:167], v[94:97]
	v_mfma_f32_16x16x32_bf16 v[98:101], v[228:231], v[168:171], v[98:101]
	v_mfma_f32_16x16x32_bf16 v[102:105], v[228:231], v[122:125], v[102:105]
	v_mfma_f32_16x16x32_bf16 v[106:109], v[232:235], v[160:163], v[106:109]
	v_mfma_f32_16x16x32_bf16 v[110:113], v[232:235], v[164:167], v[110:113]
	v_mfma_f32_16x16x32_bf16 v[114:117], v[232:235], v[168:171], v[114:117]
	v_mfma_f32_16x16x32_bf16 v[118:121], v[232:235], v[122:125], v[118:121]
	v_mfma_f32_16x16x32_bf16 v[208:211], v[236:239], v[160:163], v[208:211]
	v_mfma_f32_16x16x32_bf16 v[212:215], v[236:239], v[164:167], v[212:215]
	v_mfma_f32_16x16x32_bf16 v[216:219], v[236:239], v[168:171], v[216:219]
	v_mfma_f32_16x16x32_bf16 v[220:223], v[236:239], v[122:125], v[220:223]
	s_waitcnt vmcnt(0)
	s_barrier
	ds_read_b128 v[224:227], v126 offset:24576
	ds_read_b128 v[240:243], v128 offset:24576
	ds_read_b128 v[244:247], v128 offset:25600
	ds_read_b128 v[248:251], v128 offset:26624
	ds_read_b128 v[156:159], v128 offset:27648
	ds_read_b128 v[228:231], v126 offset:25600
	ds_read_b128 v[232:235], v126 offset:26624
	ds_read_b128 v[236:239], v126 offset:27648
	ds_read_b128 v[160:163], v128 offset:32768
	ds_read_b128 v[164:167], v128 offset:33792
	ds_read_b128 v[168:171], v128 offset:34816
	ds_read_b128 v[122:125], v128 offset:35840
	s_waitcnt lgkmcnt(10)
	v_mfma_f32_16x16x32_bf16 v[2:5], v[224:227], v[240:243], v[2:5]
	s_waitcnt lgkmcnt(9)
	v_mfma_f32_16x16x32_bf16 v[6:9], v[224:227], v[244:247], v[6:9]
	s_waitcnt lgkmcnt(8)
	v_mfma_f32_16x16x32_bf16 v[10:13], v[224:227], v[248:251], v[10:13]
	s_waitcnt lgkmcnt(7)
	v_mfma_f32_16x16x32_bf16 v[14:17], v[224:227], v[156:159], v[14:17]
	s_waitcnt lgkmcnt(6)
	v_mfma_f32_16x16x32_bf16 v[18:21], v[228:231], v[240:243], v[18:21]
	v_mfma_f32_16x16x32_bf16 v[22:25], v[228:231], v[244:247], v[22:25]
	v_mfma_f32_16x16x32_bf16 v[26:29], v[228:231], v[248:251], v[26:29]
	v_mfma_f32_16x16x32_bf16 v[30:33], v[228:231], v[156:159], v[30:33]
	s_waitcnt lgkmcnt(5)
	v_mfma_f32_16x16x32_bf16 v[34:37], v[232:235], v[240:243], v[34:37]
	v_mfma_f32_16x16x32_bf16 v[38:41], v[232:235], v[244:247], v[38:41]
	v_mfma_f32_16x16x32_bf16 v[42:45], v[232:235], v[248:251], v[42:45]
	v_mfma_f32_16x16x32_bf16 v[46:49], v[232:235], v[156:159], v[46:49]
	s_waitcnt lgkmcnt(4)
	v_mfma_f32_16x16x32_bf16 v[50:53], v[236:239], v[240:243], v[50:53]
	v_mfma_f32_16x16x32_bf16 v[54:57], v[236:239], v[244:247], v[54:57]
	v_mfma_f32_16x16x32_bf16 v[58:61], v[236:239], v[248:251], v[58:61]
	v_mfma_f32_16x16x32_bf16 v[62:65], v[236:239], v[156:159], v[62:65]
	s_waitcnt lgkmcnt(3)
	v_mfma_f32_16x16x32_bf16 v[74:77], v[224:227], v[160:163], v[74:77]
	s_waitcnt lgkmcnt(2)
	v_mfma_f32_16x16x32_bf16 v[78:81], v[224:227], v[164:167], v[78:81]
	s_waitcnt lgkmcnt(1)
	v_mfma_f32_16x16x32_bf16 v[82:85], v[224:227], v[168:171], v[82:85]
	s_waitcnt lgkmcnt(0)
	v_mfma_f32_16x16x32_bf16 v[86:89], v[224:227], v[122:125], v[86:89]
	v_mfma_f32_16x16x32_bf16 v[90:93], v[228:231], v[160:163], v[90:93]
	v_mfma_f32_16x16x32_bf16 v[94:97], v[228:231], v[164:167], v[94:97]
	v_mfma_f32_16x16x32_bf16 v[98:101], v[228:231], v[168:171], v[98:101]
	v_mfma_f32_16x16x32_bf16 v[102:105], v[228:231], v[122:125], v[102:105]
	v_mfma_f32_16x16x32_bf16 v[106:109], v[232:235], v[160:163], v[106:109]
	v_mfma_f32_16x16x32_bf16 v[110:113], v[232:235], v[164:167], v[110:113]
	v_mfma_f32_16x16x32_bf16 v[114:117], v[232:235], v[168:171], v[114:117]
	v_mfma_f32_16x16x32_bf16 v[118:121], v[232:235], v[122:125], v[118:121]
	v_mfma_f32_16x16x32_bf16 v[208:211], v[236:239], v[160:163], v[208:211]
	v_mfma_f32_16x16x32_bf16 v[212:215], v[236:239], v[164:167], v[212:215]
	v_mfma_f32_16x16x32_bf16 v[216:219], v[236:239], v[168:171], v[216:219]
	v_mfma_f32_16x16x32_bf16 v[220:223], v[236:239], v[122:125], v[220:223]
	s_barrier
	s_mov_b32 s16, 0

; #define BLOAD(A_, B_, kt) do { _Pragma("unroll") for (int i = 0; i < 4; ++i) { \
;     A_[i] = *(const u32x4*)((const char*)Ap + (aoff + (unsigned)(32 * i * lda + (kt) * 64) * 2u)); B_[i] = *(const u32x4*)((const char*)Wt + (woff + (unsigned)(32 * i * K + (kt) * 64) * 2u)); } } while (0)
; #define BLOAD(A_, B_, kt) do { _Pragma("unroll") for (int i = 0; i < 4; ++i) { \
;     A_[i] = *(const u32x4*)((const char*)Ap + (aoff + (unsigned)(32 * i * lda + (kt) * 64) * 2u)); B_[i] = *(const u32x4*)((const char*)Wt + (woff + (unsigned)(32 * i * K + (kt) * 64) * 2u)); } } while (0)
; #define BSTORE(A_, B_, buf) do { _Pragma("unroll") for (int i = 0; i < 4; ++i) { \
;     *(u32x4*)&As[(buf) * GBUF + (srow + 32 * i) * LDT + sc8] = A_[i]; \
;     *(u32x4*)&Bs[(buf) * GBUF + (srow + 32 * i) * LDT + sc8] = B_[i]; } } while (0)
; template <int NK>
; DI void gemm_run(PF& pf, const u16* __restrict__ Ap, int lda, const u16* __restrict__ Wt, f32x16 (&acc)[2][2], char* smem) {
;     ...
;   __builtin_amdgcn_s_setprio(0);
;   __syncthreads();
;   BSTORE(pf.a0, pf.b0, 0);
;   BLOAD(pf.a0, pf.b0, 2);
;   __syncthreads();
; #pragma unroll
;   for (int kt = 0; kt < nk; kt += 2) {
;     BCOMP(0);
;     BSTORE(pf.a1, pf.b1, 1);
;     if (kt + 3 < nk) BLOAD(pf.a1, pf.b1, kt + 3);
;     __syncthreads();
;     BCOMP(1);
;     if (kt + 2 < nk) { BSTORE(pf.a0, pf.b0, 0); if (kt + 4 < nk) BLOAD(pf.a0, pf.b0, kt + 4); }
;     __syncthreads();
;   }
.Lffn1_kloop:
	s_waitcnt vmcnt(6)
	s_barrier
	ds_read_b128 v[208:211], v138 offset:0
	ds_read_b128 v[224:227], v140 offset:0
	ds_read_b128 v[228:231], v140 offset:1024
	ds_read_b128 v[232:235], v140 offset:2048
	ds_read_b128 v[236:239], v140 offset:3072
	s_add_u32 m0, s42, 0xc000
	s_add_u32 s28, s28, 0x40
	s_addc_u32 s29, s29, 0
	global_load_lds_dwordx4 v142, s[28:29]
	global_load_lds_dwordx4 v143, s[28:29] offset:1024
	s_add_u32 m0, s43, 0xc000
	s_add_u32 s30, s30, 0x40000
	s_addc_u32 s31, s31, 0
	global_load_lds_dwordx4 v144, s[30:31]
	global_load_lds_dwordx4 v145, s[30:31] offset:1024
	global_load_lds_dwordx4 v146, s[30:31] offset:2048
	global_load_lds_dwordx4 v147, s[30:31] offset:3072
	ds_read_b128 v[212:215], v138 offset:1024
	ds_read_b128 v[216:219], v138 offset:2048
	ds_read_b128 v[220:223], v138 offset:3072
	ds_read_b128 v[240:243], v140 offset:8192
	ds_read_b128 v[244:247], v140 offset:9216
	ds_read_b128 v[248:251], v140 offset:10240
	ds_read_b128 v[156:159], v140 offset:11264
	s_waitcnt lgkmcnt(10)
	v_mfma_f32_16x16x32_bf16 v[2:5], v[208:211], v[224:227], v[2:5]
	s_waitcnt lgkmcnt(9)
	v_mfma_f32_16x16x32_bf16 v[6:9], v[208:211], v[228:231], v[6:9]
	s_waitcnt lgkmcnt(8)
	v_mfma_f32_16x16x32_bf16 v[10:13], v[208:211], v[232:235], v[10:13]
	s_waitcnt lgkmcnt(7)
	v_mfma_f32_16x16x32_bf16 v[14:17], v[208:211], v[236:239], v[14:17]
	s_waitcnt lgkmcnt(6)
	v_mfma_f32_16x16x32_bf16 v[18:21], v[212:215], v[224:227], v[18:21]
	v_mfma_f32_16x16x32_bf16 v[22:25], v[212:215], v[228:231], v[22:25]
	v_mfma_f32_16x16x32_bf16 v[26:29], v[212:215], v[232:235], v[26:29]
	v_mfma_f32_16x16x32_bf16 v[30:33], v[212:215], v[236:239], v[30:33]
	s_waitcnt lgkmcnt(5)
	v_mfma_f32_16x16x32_bf16 v[34:37], v[216:219], v[224:227], v[34:37]
	v_mfma_f32_16x16x32_bf16 v[38:41], v[216:219], v[228:231], v[38:41]
	v_mfma_f32_16x16x32_bf16 v[42:45], v[216:219], v[232:235], v[42:45]
	v_mfma_f32_16x16x32_bf16 v[46:49], v[216:219], v[236:239], v[46:49]
	s_waitcnt lgkmcnt(4)
	v_mfma_f32_16x16x32_bf16 v[50:53], v[220:223], v[224:227], v[50:53]
	v_mfma_f32_16x16x32_bf16 v[54:57], v[220:223], v[228:231], v[54:57]
	v_mfma_f32_16x16x32_bf16 v[58:61], v[220:223], v[232:235], v[58:61]
	v_mfma_f32_16x16x32_bf16 v[62:65], v[220:223], v[236:239], v[62:65]
	s_waitcnt lgkmcnt(3)
	v_mfma_f32_16x16x32_bf16 v[74:77], v[208:211], v[240:243], v[74:77]
	s_waitcnt lgkmcnt(2)
	v_mfma_f32_16x16x32_bf16 v[78:81], v[208:211], v[244:247], v[78:81]
	s_waitcnt lgkmcnt(1)
	v_mfma_f32_16x16x32_bf16 v[82:85], v[208:211], v[248:251], v[82:85]
	s_waitcnt lgkmcnt(0)
	v_mfma_f32_16x16x32_bf16 v[86:89], v[208:211], v[156:159], v[86:89]
	v_mfma_f32_16x16x32_bf16 v[90:93], v[212:215], v[240:243], v[90:93]
	v_mfma_f32_16x16x32_bf16 v[94:97], v[212:215], v[244:247], v[94:97]
	v_mfma_f32_16x16x32_bf16 v[98:101], v[212:215], v[248:251], v[98:101]
	v_mfma_f32_16x16x32_bf16 v[102:105], v[212:215], v[156:159], v[102:105]
	v_mfma_f32_16x16x32_bf16 v[106:109], v[216:219], v[240:243], v[106:109]
	v_mfma_f32_16x16x32_bf16 v[110:113], v[216:219], v[244:247], v[110:113]
	v_mfma_f32_16x16x32_bf16 v[114:117], v[216:219], v[248:251], v[114:117]
	v_mfma_f32_16x16x32_bf16 v[118:121], v[216:219], v[156:159], v[118:121]
	v_mfma_f32_16x16x32_bf16 v[122:125], v[220:223], v[240:243], v[122:125]
	v_mfma_f32_16x16x32_bf16 v[126:129], v[220:223], v[244:247], v[126:129]
	v_mfma_f32_16x16x32_bf16 v[130:133], v[220:223], v[248:251], v[130:133]
	v_mfma_f32_16x16x32_bf16 v[134:137], v[220:223], v[156:159], v[134:137]
	s_waitcnt vmcnt(6)
	s_barrier
	ds_read_b128 v[208:211], v138 offset:24576
	ds_read_b128 v[224:227], v140 offset:24576
	ds_read_b128 v[228:231], v140 offset:25600
	ds_read_b128 v[232:235], v140 offset:26624
	ds_read_b128 v[236:239], v140 offset:27648
	s_add_u32 m0, s42, 0x0
	s_add_u32 s28, s28, 0x40
	s_addc_u32 s29, s29, 0
	global_load_lds_dwordx4 v142, s[28:29]
	global_load_lds_dwordx4 v143, s[28:29] offset:1024
	s_add_u32 m0, s43, 0x0
	s_add_u32 s30, s30, 0x40000
	s_addc_u32 s31, s31, 0
	global_load_lds_dwordx4 v144, s[30:31]
	global_load_lds_dwordx4 v145, s[30:31] offset:1024
	global_load_lds_dwordx4 v146, s[30:31] offset:2048
	global_load_lds_dwordx4 v147, s[30:31] offset:3072
	ds_read_b128 v[212:215], v138 offset:25600
	ds_read_b128 v[216:219], v138 offset:26624
	ds_read_b128 v[220:223], v138 offset:27648
	ds_read_b128 v[240:243], v140 offset:32768
	ds_read_b128 v[244:247], v140 offset:33792
	ds_read_b128 v[248:251], v140 offset:34816
	ds_read_b128 v[156:159], v140 offset:35840
	s_waitcnt lgkmcnt(10)
	v_mfma_f32_16x16x32_bf16 v[2:5], v[208:211], v[224:227], v[2:5]
	s_waitcnt lgkmcnt(9)
	v_mfma_f32_16x16x32_bf16 v[6:9], v[208:211], v[228:231], v[6:9]
	s_waitcnt lgkmcnt(8)
	v_mfma_f32_16x16x32_bf16 v[10:13], v[208:211], v[232:235], v[10:13]
	s_waitcnt lgkmcnt(7)
	v_mfma_f32_16x16x32_bf16 v[14:17], v[208:211], v[236:239], v[14:17]
	s_waitcnt lgkmcnt(6)
	v_mfma_f32_16x16x32_bf16 v[18:21], v[212:215], v[224:227], v[18:21]
	v_mfma_f32_16x16x32_bf16 v[22:25], v[212:215], v[228:231], v[22:25]
	v_mfma_f32_16x16x32_bf16 v[26:29], v[212:215], v[232:235], v[26:29]
	v_mfma_f32_16x16x32_bf16 v[30:33], v[212:215], v[236:239], v[30:33]
	s_waitcnt lgkmcnt(5)
	v_mfma_f32_16x16x32_bf16 v[34:37], v[216:219], v[224:227], v[34:37]
	v_mfma_f32_16x16x32_bf16 v[38:41], v[216:219], v[228:231], v[38:41]
	v_mfma_f32_16x16x32_bf16 v[42:45], v[216:219], v[232:235], v[42:45]
	v_mfma_f32_16x16x32_bf16 v[46:49], v[216:219], v[236:239], v[46:49]
	s_waitcnt lgkmcnt(4)
	v_mfma_f32_16x16x32_bf16 v[50:53], v[220:223], v[224:227], v[50:53]
	v_mfma_f32_16x16x32_bf16 v[54:57], v[220:223], v[228:231], v[54:57]
	v_mfma_f32_16x16x32_bf16 v[58:61], v[220:223], v[232:235], v[58:61]
	v_mfma_f32_16x16x32_bf16 v[62:65], v[220:223], v[236:239], v[62:65]
	s_waitcnt lgkmcnt(3)
	v_mfma_f32_16x16x32_bf16 v[74:77], v[208:211], v[240:243], v[74:77]
	s_waitcnt lgkmcnt(2)
	v_mfma_f32_16x16x32_bf16 v[78:81], v[208:211], v[244:247], v[78:81]
	s_waitcnt lgkmcnt(1)
	v_mfma_f32_16x16x32_bf16 v[82:85], v[208:211], v[248:251], v[82:85]
	s_waitcnt lgkmcnt(0)
	v_mfma_f32_16x16x32_bf16 v[86:89], v[208:211], v[156:159], v[86:89]
	v_mfma_f32_16x16x32_bf16 v[90:93], v[212:215], v[240:243], v[90:93]
	v_mfma_f32_16x16x32_bf16 v[94:97], v[212:215], v[244:247], v[94:97]
	v_mfma_f32_16x16x32_bf16 v[98:101], v[212:215], v[248:251], v[98:101]
	v_mfma_f32_16x16x32_bf16 v[102:105], v[212:215], v[156:159], v[102:105]
	v_mfma_f32_16x16x32_bf16 v[106:109], v[216:219], v[240:243], v[106:109]
	v_mfma_f32_16x16x32_bf16 v[110:113], v[216:219], v[244:247], v[110:113]
	v_mfma_f32_16x16x32_bf16 v[114:117], v[216:219], v[248:251], v[114:117]
	v_mfma_f32_16x16x32_bf16 v[118:121], v[216:219], v[156:159], v[118:121]
	v_mfma_f32_16x16x32_bf16 v[122:125], v[220:223], v[240:243], v[122:125]
	v_mfma_f32_16x16x32_bf16 v[126:129], v[220:223], v[244:247], v[126:129]
	v_mfma_f32_16x16x32_bf16 v[130:133], v[220:223], v[248:251], v[130:133]
	v_mfma_f32_16x16x32_bf16 v[134:137], v[220:223], v[156:159], v[134:137]
	s_waitcnt vmcnt(6)
	s_barrier
; #define BLOAD(A_, B_, kt) do { _Pragma("unroll") for (int i = 0; i < 4; ++i) { \
;     A_[i] = *(const u32x4*)((const char*)Ap + (aoff + (unsigned)(32 * i * lda + (kt) * 64) * 2u)); B_[i] = *(const u32x4*)((const char*)Wt + (woff + (unsigned)(32 * i * K + (kt) * 64) * 2u)); } } while (0)
; #define BLOAD(A_, B_, kt) do { _Pragma("unroll") for (int i = 0; i < 4; ++i) { \
;     A_[i] = *(const u32x4*)((const char*)Ap + (aoff + (unsigned)(32 * i * lda + (kt) * 64) * 2u)); B_[i] = *(const u32x4*)((const char*)Wt + (woff + (unsigned)(32 * i * K + (kt) * 64) * 2u)); } } while (0)
; #define BSTORE(A_, B_, buf) do { _Pragma("unroll") for (int i = 0; i < 4; ++i) { \
;     *(u32x4*)&As[(buf) * GBUF + (srow + 32 * i) * LDT + sc8] = A_[i]; \
;     *(u32x4*)&Bs[(buf) * GBUF + (srow + 32 * i) * LDT + sc8] = B_[i]; } } while (0)
; template <int NK>
; DI void gemm_run(PF& pf, const u16* __restrict__ Ap, int lda, const u16* __restrict__ Wt, f32x16 (&acc)[2][2], char* smem) {
;     ...
;   __builtin_amdgcn_s_setprio(0);
;   __syncthreads();
;   BSTORE(pf.a0, pf.b0, 0);
;   BLOAD(pf.a0, pf.b0, 2);
;   __syncthreads();
; #pragma unroll
;   for (int kt = 0; kt < nk; kt += 2) {
;     BCOMP(0);
;     BSTORE(pf.a1, pf.b1, 1);
;     if (kt + 3 < nk) BLOAD(pf.a1, pf.b1, kt + 3);
;     __syncthreads();
;     BCOMP(1);
;     if (kt + 2 < nk) { BSTORE(pf.a0, pf.b0, 0); if (kt + 4 < nk) BLOAD(pf.a0, pf.b0, kt + 4); }
;     __syncthreads();
;   }
	ds_read_b128 v[208:211], v138 offset:49152
	ds_read_b128 v[224:227], v140 offset:49152
	ds_read_b128 v[228:231], v140 offset:50176
	ds_read_b128 v[232:235], v140 offset:51200
	ds_read_b128 v[236:239], v140 offset:52224
	s_add_u32 m0, s42, 0x6000
	s_add_u32 s28, s28, 0x40
	s_addc_u32 s29, s29, 0
	global_load_lds_dwordx4 v142, s[28:29]
	global_load_lds_dwordx4 v143, s[28:29] offset:1024
	s_add_u32 m0, s43, 0x6000
	s_add_u32 s30, s30, 0x40000
	s_addc_u32 s31, s31, 0
	global_load_lds_dwordx4 v144, s[30:31]
	global_load_lds_dwordx4 v145, s[30:31] offset:1024
	global_load_lds_dwordx4 v146, s[30:31] offset:2048
	global_load_lds_dwordx4 v147, s[30:31] offset:3072
	ds_read_b128 v[212:215], v138 offset:50176
	ds_read_b128 v[216:219], v138 offset:51200
	ds_read_b128 v[220:223], v138 offset:52224
	ds_read_b128 v[240:243], v140 offset:57344
	ds_read_b128 v[244:247], v140 offset:58368
	ds_read_b128 v[248:251], v140 offset:59392
	ds_read_b128 v[156:159], v140 offset:60416
	s_waitcnt lgkmcnt(10)
	v_mfma_f32_16x16x32_bf16 v[2:5], v[208:211], v[224:227], v[2:5]
	s_waitcnt lgkmcnt(9)
	v_mfma_f32_16x16x32_bf16 v[6:9], v[208:211], v[228:231], v[6:9]
	s_waitcnt lgkmcnt(8)
	v_mfma_f32_16x16x32_bf16 v[10:13], v[208:211], v[232:235], v[10:13]
	s_waitcnt lgkmcnt(7)
	v_mfma_f32_16x16x32_bf16 v[14:17], v[208:211], v[236:239], v[14:17]
	s_waitcnt lgkmcnt(6)
	v_mfma_f32_16x16x32_bf16 v[18:21], v[212:215], v[224:227], v[18:21]
	v_mfma_f32_16x16x32_bf16 v[22:25], v[212:215], v[228:231], v[22:25]
	v_mfma_f32_16x16x32_bf16 v[26:29], v[212:215], v[232:235], v[26:29]
	v_mfma_f32_16x16x32_bf16 v[30:33], v[212:215], v[236:239], v[30:33]
	s_waitcnt lgkmcnt(5)
	v_mfma_f32_16x16x32_bf16 v[34:37], v[216:219], v[224:227], v[34:37]
	v_mfma_f32_16x16x32_bf16 v[38:41], v[216:219], v[228:231], v[38:41]
	v_mfma_f32_16x16x32_bf16 v[42:45], v[216:219], v[232:235], v[42:45]
	v_mfma_f32_16x16x32_bf16 v[46:49], v[216:219], v[236:239], v[46:49]
	s_waitcnt lgkmcnt(4)
	v_mfma_f32_16x16x32_bf16 v[50:53], v[220:223], v[224:227], v[50:53]
	v_mfma_f32_16x16x32_bf16 v[54:57], v[220:223], v[228:231], v[54:57]
	v_mfma_f32_16x16x32_bf16 v[58:61], v[220:223], v[232:235], v[58:61]
	v_mfma_f32_16x16x32_bf16 v[62:65], v[220:223], v[236:239], v[62:65]
	s_waitcnt lgkmcnt(3)
	v_mfma_f32_16x16x32_bf16 v[74:77], v[208:211], v[240:243], v[74:77]
	s_waitcnt lgkmcnt(2)
	v_mfma_f32_16x16x32_bf16 v[78:81], v[208:211], v[244:247], v[78:81]
	s_waitcnt lgkmcnt(1)
	v_mfma_f32_16x16x32_bf16 v[82:85], v[208:211], v[248:251], v[82:85]
	s_waitcnt lgkmcnt(0)
	v_mfma_f32_16x16x32_bf16 v[86:89], v[208:211], v[156:159], v[86:89]
	v_mfma_f32_16x16x32_bf16 v[90:93], v[212:215], v[240:243], v[90:93]
	v_mfma_f32_16x16x32_bf16 v[94:97], v[212:215], v[244:247], v[94:97]
	v_mfma_f32_16x16x32_bf16 v[98:101], v[212:215], v[248:251], v[98:101]
	v_mfma_f32_16x16x32_bf16 v[102:105], v[212:215], v[156:159], v[102:105]
	v_mfma_f32_16x16x32_bf16 v[106:109], v[216:219], v[240:243], v[106:109]
	v_mfma_f32_16x16x32_bf16 v[110:113], v[216:219], v[244:247], v[110:113]
	v_mfma_f32_16x16x32_bf16 v[114:117], v[216:219], v[248:251], v[114:117]
	v_mfma_f32_16x16x32_bf16 v[118:121], v[216:219], v[156:159], v[118:121]
	v_mfma_f32_16x16x32_bf16 v[122:125], v[220:223], v[240:243], v[122:125]
	v_mfma_f32_16x16x32_bf16 v[126:129], v[220:223], v[244:247], v[126:129]
	v_mfma_f32_16x16x32_bf16 v[130:133], v[220:223], v[248:251], v[130:133]
	v_mfma_f32_16x16x32_bf16 v[134:137], v[220:223], v[156:159], v[134:137]
	s_sub_u32 s46, s46, 1
	s_cmp_lg_u32 s46, 0
	s_cbranch_scc1 .Lffn1_kloop
	s_waitcnt vmcnt(6)
	s_barrier
; #define BLOAD(A_, B_, kt) do { _Pragma("unroll") for (int i = 0; i < 4; ++i) { \
;     A_[i] = *(const u32x4*)((const char*)Ap + (aoff + (unsigned)(32 * i * lda + (kt) * 64) * 2u)); B_[i] = *(const u32x4*)((const char*)Wt + (woff + (unsigned)(32 * i * K + (kt) * 64) * 2u)); } } while (0)
; #define BLOAD(A_, B_, kt) do { _Pragma("unroll") for (int i = 0; i < 4; ++i) { \
;     A_[i] = *(const u32x4*)((const char*)Ap + (aoff + (unsigned)(32 * i * lda + (kt) * 64) * 2u)); B_[i] = *(const u32x4*)((const char*)Wt + (woff + (unsigned)(32 * i * K + (kt) * 64) * 2u)); } } while (0)
; #define BSTORE(A_, B_, buf) do { _Pragma("unroll") for (int i = 0; i < 4; ++i) { \
;     *(u32x4*)&As[(buf) * GBUF + (srow + 32 * i) * LDT + sc8] = A_[i]; \
;     *(u32x4*)&Bs[(buf) * GBUF + (srow + 32 * i) * LDT + sc8] = B_[i]; } } while (0)
; template <int NK>
; DI void gemm_run(PF& pf, const u16* __restrict__ Ap, int lda, const u16* __restrict__ Wt, f32x16 (&acc)[2][2], char* smem) {
;     ...
;   __builtin_amdgcn_s_setprio(0);
;   __syncthreads();
;   BSTORE(pf.a0, pf.b0, 0);
;   BLOAD(pf.a0, pf.b0, 2);
;   __syncthreads();
; #pragma unroll
;   for (int kt = 0; kt < nk; kt += 2) {
;     BCOMP(0);
;     BSTORE(pf.a1, pf.b1, 1);
;     if (kt + 3 < nk) BLOAD(pf.a1, pf.b1, kt + 3);
;     __syncthreads();
;     BCOMP(1);
;     if (kt + 2 < nk) { BSTORE(pf.a0, pf.b0, 0); if (kt + 4 < nk) BLOAD(pf.a0, pf.b0, kt + 4); }
;     __syncthreads();
;   }
	ds_read_b128 v[208:211], v138 offset:0
	ds_read_b128 v[224:227], v140 offset:0
	ds_read_b128 v[228:231], v140 offset:1024
	ds_read_b128 v[232:235], v140 offset:2048
	ds_read_b128 v[236:239], v140 offset:3072
	ds_read_b128 v[212:215], v138 offset:1024
	ds_read_b128 v[216:219], v138 offset:2048
	ds_read_b128 v[220:223], v138 offset:3072
	ds_read_b128 v[240:243], v140 offset:8192
	ds_read_b128 v[244:247], v140 offset:9216
	ds_read_b128 v[248:251], v140 offset:10240
	ds_read_b128 v[156:159], v140 offset:11264
	s_waitcnt lgkmcnt(10)
	v_mfma_f32_16x16x32_bf16 v[2:5], v[208:211], v[224:227], v[2:5]
	s_waitcnt lgkmcnt(9)
	v_mfma_f32_16x16x32_bf16 v[6:9], v[208:211], v[228:231], v[6:9]
	s_waitcnt lgkmcnt(8)
	v_mfma_f32_16x16x32_bf16 v[10:13], v[208:211], v[232:235], v[10:13]
	s_waitcnt lgkmcnt(7)
	v_mfma_f32_16x16x32_bf16 v[14:17], v[208:211], v[236:239], v[14:17]
	s_waitcnt lgkmcnt(6)
	v_mfma_f32_16x16x32_bf16 v[18:21], v[212:215], v[224:227], v[18:21]
	v_mfma_f32_16x16x32_bf16 v[22:25], v[212:215], v[228:231], v[22:25]
	v_mfma_f32_16x16x32_bf16 v[26:29], v[212:215], v[232:235], v[26:29]
	v_mfma_f32_16x16x32_bf16 v[30:33], v[212:215], v[236:239], v[30:33]
	s_waitcnt lgkmcnt(5)
	v_mfma_f32_16x16x32_bf16 v[34:37], v[216:219], v[224:227], v[34:37]
	v_mfma_f32_16x16x32_bf16 v[38:41], v[216:219], v[228:231], v[38:41]
	v_mfma_f32_16x16x32_bf16 v[42:45], v[216:219], v[232:235], v[42:45]
	v_mfma_f32_16x16x32_bf16 v[46:49], v[216:219], v[236:239], v[46:49]
	s_waitcnt lgkmcnt(4)
	v_mfma_f32_16x16x32_bf16 v[50:53], v[220:223], v[224:227], v[50:53]
	v_mfma_f32_16x16x32_bf16 v[54:57], v[220:223], v[228:231], v[54:57]
	v_mfma_f32_16x16x32_bf16 v[58:61], v[220:223], v[232:235], v[58:61]
	v_mfma_f32_16x16x32_bf16 v[62:65], v[220:223], v[236:239], v[62:65]
	s_waitcnt lgkmcnt(3)
	v_mfma_f32_16x16x32_bf16 v[74:77], v[208:211], v[240:243], v[74:77]
	s_waitcnt lgkmcnt(2)
	v_mfma_f32_16x16x32_bf16 v[78:81], v[208:211], v[244:247], v[78:81]
	s_waitcnt lgkmcnt(1)
	v_mfma_f32_16x16x32_bf16 v[82:85], v[208:211], v[248:251], v[82:85]
	s_waitcnt lgkmcnt(0)
	v_mfma_f32_16x16x32_bf16 v[86:89], v[208:211], v[156:159], v[86:89]
	v_mfma_f32_16x16x32_bf16 v[90:93], v[212:215], v[240:243], v[90:93]
	v_mfma_f32_16x16x32_bf16 v[94:97], v[212:215], v[244:247], v[94:97]
	v_mfma_f32_16x16x32_bf16 v[98:101], v[212:215], v[248:251], v[98:101]
	v_mfma_f32_16x16x32_bf16 v[102:105], v[212:215], v[156:159], v[102:105]
	v_mfma_f32_16x16x32_bf16 v[106:109], v[216:219], v[240:243], v[106:109]
	v_mfma_f32_16x16x32_bf16 v[110:113], v[216:219], v[244:247], v[110:113]
	v_mfma_f32_16x16x32_bf16 v[114:117], v[216:219], v[248:251], v[114:117]
	v_mfma_f32_16x16x32_bf16 v[118:121], v[216:219], v[156:159], v[118:121]
	v_mfma_f32_16x16x32_bf16 v[122:125], v[220:223], v[240:243], v[122:125]
	v_mfma_f32_16x16x32_bf16 v[126:129], v[220:223], v[244:247], v[126:129]
	v_mfma_f32_16x16x32_bf16 v[130:133], v[220:223], v[248:251], v[130:133]
	v_mfma_f32_16x16x32_bf16 v[134:137], v[220:223], v[156:159], v[134:137]
	s_waitcnt vmcnt(0)
	s_barrier
	ds_read_b128 v[208:211], v138 offset:24576
	ds_read_b128 v[224:227], v140 offset:24576
	ds_read_b128 v[228:231], v140 offset:25600
	ds_read_b128 v[232:235], v140 offset:26624
	ds_read_b128 v[236:239], v140 offset:27648
	ds_read_b128 v[212:215], v138 offset:25600
	ds_read_b128 v[216:219], v138 offset:26624
	ds_read_b128 v[220:223], v138 offset:27648
	ds_read_b128 v[240:243], v140 offset:32768
	ds_read_b128 v[244:247], v140 offset:33792
	ds_read_b128 v[248:251], v140 offset:34816
	ds_read_b128 v[156:159], v140 offset:35840
	s_waitcnt lgkmcnt(10)
	v_mfma_f32_16x16x32_bf16 v[2:5], v[208:211], v[224:227], v[2:5]
	s_waitcnt lgkmcnt(9)
	v_mfma_f32_16x16x32_bf16 v[6:9], v[208:211], v[228:231], v[6:9]
	s_waitcnt lgkmcnt(8)
	v_mfma_f32_16x16x32_bf16 v[10:13], v[208:211], v[232:235], v[10:13]
	s_waitcnt lgkmcnt(7)
	v_mfma_f32_16x16x32_bf16 v[14:17], v[208:211], v[236:239], v[14:17]
	s_waitcnt lgkmcnt(6)
	v_mfma_f32_16x16x32_bf16 v[18:21], v[212:215], v[224:227], v[18:21]
	v_mfma_f32_16x16x32_bf16 v[22:25], v[212:215], v[228:231], v[22:25]
	v_mfma_f32_16x16x32_bf16 v[26:29], v[212:215], v[232:235], v[26:29]
	v_mfma_f32_16x16x32_bf16 v[30:33], v[212:215], v[236:239], v[30:33]
	s_waitcnt lgkmcnt(5)
	v_mfma_f32_16x16x32_bf16 v[34:37], v[216:219], v[224:227], v[34:37]
	v_mfma_f32_16x16x32_bf16 v[38:41], v[216:219], v[228:231], v[38:41]
	v_mfma_f32_16x16x32_bf16 v[42:45], v[216:219], v[232:235], v[42:45]
	v_mfma_f32_16x16x32_bf16 v[46:49], v[216:219], v[236:239], v[46:49]
	s_waitcnt lgkmcnt(4)
	v_mfma_f32_16x16x32_bf16 v[50:53], v[220:223], v[224:227], v[50:53]
	v_mfma_f32_16x16x32_bf16 v[54:57], v[220:223], v[228:231], v[54:57]
	v_mfma_f32_16x16x32_bf16 v[58:61], v[220:223], v[232:235], v[58:61]
	v_mfma_f32_16x16x32_bf16 v[62:65], v[220:223], v[236:239], v[62:65]
	s_waitcnt lgkmcnt(3)
	v_mfma_f32_16x16x32_bf16 v[74:77], v[208:211], v[240:243], v[74:77]
	s_waitcnt lgkmcnt(2)
	v_mfma_f32_16x16x32_bf16 v[78:81], v[208:211], v[244:247], v[78:81]
	s_waitcnt lgkmcnt(1)
	v_mfma_f32_16x16x32_bf16 v[82:85], v[208:211], v[248:251], v[82:85]
	s_waitcnt lgkmcnt(0)
	v_mfma_f32_16x16x32_bf16 v[86:89], v[208:211], v[156:159], v[86:89]
	v_mfma_f32_16x16x32_bf16 v[90:93], v[212:215], v[240:243], v[90:93]
	v_mfma_f32_16x16x32_bf16 v[94:97], v[212:215], v[244:247], v[94:97]
	v_mfma_f32_16x16x32_bf16 v[98:101], v[212:215], v[248:251], v[98:101]
	v_mfma_f32_16x16x32_bf16 v[102:105], v[212:215], v[156:159], v[102:105]
	v_mfma_f32_16x16x32_bf16 v[106:109], v[216:219], v[240:243], v[106:109]
	v_mfma_f32_16x16x32_bf16 v[110:113], v[216:219], v[244:247], v[110:113]
	v_mfma_f32_16x16x32_bf16 v[114:117], v[216:219], v[248:251], v[114:117]
	v_mfma_f32_16x16x32_bf16 v[118:121], v[216:219], v[156:159], v[118:121]
	v_mfma_f32_16x16x32_bf16 v[122:125], v[220:223], v[240:243], v[122:125]
	v_mfma_f32_16x16x32_bf16 v[126:129], v[220:223], v[244:247], v[126:129]
	v_mfma_f32_16x16x32_bf16 v[130:133], v[220:223], v[248:251], v[130:133]
	v_mfma_f32_16x16x32_bf16 v[134:137], v[220:223], v[156:159], v[134:137]
	s_barrier

; #define MFMA(a, b, c) __builtin_amdgcn_mfma_f32_32x32x16_bf16((a), (b), (c), 0, 0, 0)
; DI float xhalf_max(float x) { const auto rr = __builtin_amdgcn_permlane32_swap(__float_as_uint(x), __float_as_uint(x), false, false); return fmaxf(__uint_as_float(rr[0]), __uint_as_float(rr[1])); }
; template <int DQK, int DV, bool BAND> ...
;     ...
;       __builtin_amdgcn_s_setprio(1);
; #pragma unroll
;       for (int d0 = 0; d0 < ND0; ++d0) {
;         const bf16x8 k0f = *(const bf16x8*)&Ks[r32 * KLD + d0 * 16 + hi * 8];
;         const bf16x8 k1f = *(const bf16x8*)&Ks[(32 + r32) * KLD + d0 * 16 + hi * 8];
;         p0 = MFMA(k0f, qf[d0], p0); p1 = MFMA(k1f, qf[d0], p1);
;       }
;       __builtin_amdgcn_s_setprio(0);
;       float mx = fmaxf(p0[0], p1[0]);
; #pragma unroll
;       for (int r = 1; r < 16; ++r) mx = fmaxf(mx, fmaxf(p0[r], p1[r]));
;       mx = xhalf_max(mx);
;       if (__builtin_amdgcn_ballot_w64(mx > m_run + 8.f) != 0ull) {
.LBB1_320:
	s_setprio 1
	ds_read_b128 v[34:37], v132
	ds_read_b128 v[134:137], v132 offset:32
	ds_read_b128 v[50:53], v132 offset:6656
	s_waitcnt lgkmcnt(2)
	v_mfma_f32_32x32x16_bf16 v[34:49], v[34:37], v[66:69], 0
	s_waitcnt lgkmcnt(1)
	v_mfma_f32_32x32x16_bf16 v[34:49], v[134:137], v[70:73], v[34:49]
	ds_read_b128 v[134:137], v132 offset:6688
	s_waitcnt lgkmcnt(1)
	v_mfma_f32_32x32x16_bf16 v[50:65], v[50:53], v[66:69], 0
	s_waitcnt lgkmcnt(0)
	v_mfma_f32_32x32x16_bf16 v[50:65], v[134:137], v[70:73], v[50:65]
	ds_read_b128 v[134:137], v132 offset:64
	s_waitcnt lgkmcnt(0)
	v_mfma_f32_32x32x16_bf16 v[34:49], v[134:137], v[74:77], v[34:49]
	ds_read_b128 v[134:137], v132 offset:6720
	s_waitcnt lgkmcnt(0)
	v_mfma_f32_32x32x16_bf16 v[50:65], v[134:137], v[74:77], v[50:65]
	ds_read_b128 v[134:137], v132 offset:96
	s_waitcnt lgkmcnt(0)
	v_mfma_f32_32x32x16_bf16 v[34:49], v[134:137], v[78:81], v[34:49]
	ds_read_b128 v[134:137], v132 offset:6752
	s_waitcnt lgkmcnt(0)
	v_mfma_f32_32x32x16_bf16 v[50:65], v[134:137], v[78:81], v[50:65]
	ds_read_b128 v[134:137], v132 offset:128
	s_waitcnt lgkmcnt(0)
	v_mfma_f32_32x32x16_bf16 v[34:49], v[134:137], v[82:85], v[34:49]
	ds_read_b128 v[134:137], v132 offset:6784
	s_waitcnt lgkmcnt(0)
	v_mfma_f32_32x32x16_bf16 v[50:65], v[134:137], v[82:85], v[50:65]
	ds_read_b128 v[134:137], v132 offset:160
	s_waitcnt lgkmcnt(0)
	v_mfma_f32_32x32x16_bf16 v[34:49], v[134:137], v[86:89], v[34:49]
	ds_read_b128 v[134:137], v132 offset:6816
	s_waitcnt lgkmcnt(0)
	v_mfma_f32_32x32x16_bf16 v[50:65], v[134:137], v[86:89], v[50:65]
	s_setprio 0
	s_nop 10
	v_max3_f32 v0, v34, v50, v35
	v_max3_f32 v134, v51, v36, v52
	v_max3_f32 v0, v0, v37, v53
	v_max3_f32 v134, v134, v38, v54
	v_max3_f32 v0, v0, v39, v55
	v_max3_f32 v134, v134, v40, v56
	v_max3_f32 v0, v0, v41, v57
	v_max3_f32 v134, v134, v42, v58
	v_max3_f32 v0, v0, v43, v59
	v_max3_f32 v134, v134, v44, v60
	v_max3_f32 v0, v0, v45, v61
	v_max3_f32 v134, v134, v46, v62
	v_max3_f32 v0, v0, v47, v63
	v_max3_f32 v134, v134, v48, v64
	v_max3_f32 v0, v0, v49, v65
	v_max_f32_e32 v0, v0, v134
	v_mov_b32_e32 v134, v0
	s_nop 1
	v_permlane32_swap_b32_e32 v0, v134
	v_max_f32_e32 v0, v0, v134
	v_add_f32_e32 v134, 0x41000000, v133
	v_cmp_gt_f32_e32 vcc, v0, v134
	s_cbranch_vccz .LBB1_324
	v_max_f32_e32 v0, v0, v0
	v_max_f32_e32 v134, v133, v133
	v_max_f32_e32 v0, v134, v0
	v_cmp_neq_f32_e32 vcc, s7, v0
	s_nop 1
	v_cndmask_b32_e32 v134, 0, v0, vcc
	v_sub_f32_e32 v133, v133, v134
	v_exp_f32_e32 v133, v133
	s_and_saveexec_b64 s[22:23], s[36:37]
	ds_write_b32 v124, v133 offset:34816
	s_or_b64 exec, exec, s[22:23]
	ds_read_b128 v[134:137], v120 offset:34816
	ds_read_b128 v[138:141], v120 offset:34848
	ds_read_b128 v[142:145], v120 offset:34880
	ds_read_b128 v[146:149], v120 offset:34912
	v_mul_f32_e32 v126, v126, v133
	s_waitcnt lgkmcnt(3)
	v_pk_mul_f32 v[20:21], v[20:21], v[136:137]
	s_waitcnt lgkmcnt(2)
	v_pk_mul_f32 v[24:25], v[24:25], v[140:141]
	s_waitcnt lgkmcnt(1)
	v_pk_mul_f32 v[28:29], v[28:29], v[144:145]
	s_waitcnt lgkmcnt(0)
	v_pk_mul_f32 v[32:33], v[32:33], v[148:149]
	v_pk_mul_f32 v[16:17], v[16:17], v[148:149]
	v_pk_mul_f32 v[12:13], v[12:13], v[144:145]
	v_pk_mul_f32 v[8:9], v[8:9], v[140:141]
	v_pk_mul_f32 v[4:5], v[4:5], v[136:137]
	v_pk_mul_f32 v[30:31], v[30:31], v[146:147]
	v_pk_mul_f32 v[26:27], v[26:27], v[142:143]
	v_pk_mul_f32 v[22:23], v[22:23], v[138:139]
	v_pk_mul_f32 v[18:19], v[18:19], v[134:135]
	v_pk_mul_f32 v[14:15], v[14:15], v[146:147]
	v_pk_mul_f32 v[10:11], v[10:11], v[142:143]
	v_pk_mul_f32 v[6:7], v[6:7], v[138:139]
	v_pk_mul_f32 v[2:3], v[2:3], v[134:135]
	s_branch .LBB1_325

; #define BLOAD(A_, B_, kt) do { _Pragma("unroll") for (int i = 0; i < 4; ++i) { \
;     A_[i] = *(const u32x4*)((const char*)Ap + (aoff + (unsigned)(32 * i * lda + (kt) * 64) * 2u)); B_[i] = *(const u32x4*)((const char*)Wt + (woff + (unsigned)(32 * i * K + (kt) * 64) * 2u)); } } while (0)
; #define BLOAD(A_, B_, kt) do { _Pragma("unroll") for (int i = 0; i < 4; ++i) { \
;     A_[i] = *(const u32x4*)((const char*)Ap + (aoff + (unsigned)(32 * i * lda + (kt) * 64) * 2u)); B_[i] = *(const u32x4*)((const char*)Wt + (woff + (unsigned)(32 * i * K + (kt) * 64) * 2u)); } } while (0)
; #define BSTORE(A_, B_, buf) do { _Pragma("unroll") for (int i = 0; i < 4; ++i) { \
;     *(u32x4*)&As[(buf) * GBUF + (srow + 32 * i) * LDT + sc8] = A_[i]; \
;     *(u32x4*)&Bs[(buf) * GBUF + (srow + 32 * i) * LDT + sc8] = B_[i]; } } while (0)
; template <int NK>
; DI void gemm_run(PF& pf, const u16* __restrict__ Ap, int lda, const u16* __restrict__ Wt, f32x16 (&acc)[2][2], char* smem) {
;     ...
;   __builtin_amdgcn_s_setprio(0);
;   __syncthreads();
;   BSTORE(pf.a0, pf.b0, 0);
;   BLOAD(pf.a0, pf.b0, 2);
;   __syncthreads();
; #pragma unroll
;   for (int kt = 0; kt < nk; kt += 2) {
;     BCOMP(0);
;     BSTORE(pf.a1, pf.b1, 1);
;     if (kt + 3 < nk) BLOAD(pf.a1, pf.b1, kt + 3);
;     __syncthreads();
;     BCOMP(1);
;     if (kt + 2 < nk) { BSTORE(pf.a0, pf.b0, 0); if (kt + 4 < nk) BLOAD(pf.a0, pf.b0, kt + 4); }
;     __syncthreads();
;   }
.Linp_kloop:
	s_waitcnt vmcnt(6)
	s_barrier
	ds_read_b128 v[224:227], v126 offset:0
	ds_read_b128 v[240:243], v128 offset:0
	ds_read_b128 v[244:247], v128 offset:1024
	ds_read_b128 v[248:251], v128 offset:2048
	ds_read_b128 v[156:159], v128 offset:3072
	s_add_u32 m0, s46, 0xc000
	s_add_u32 s48, s48, 0x40
	s_addc_u32 s49, s49, 0
	global_load_lds_dwordx4 v138, s[48:49]
	global_load_lds_dwordx4 v139, s[48:49] offset:1024
	s_add_u32 m0, s47, 0xc000
	s_add_u32 s50, s50, s13
	s_addc_u32 s51, s51, 0
	global_load_lds_dwordx4 v140, s[50:51]
	global_load_lds_dwordx4 v141, s[50:51] offset:1024
	global_load_lds_dwordx4 v142, s[50:51] offset:2048
	global_load_lds_dwordx4 v143, s[50:51] offset:3072
	ds_read_b128 v[228:231], v126 offset:1024
	ds_read_b128 v[232:235], v126 offset:2048
	ds_read_b128 v[236:239], v126 offset:3072
	ds_read_b128 v[160:163], v128 offset:8192
	ds_read_b128 v[164:167], v128 offset:9216
	ds_read_b128 v[168:171], v128 offset:10240
	ds_read_b128 v[122:125], v128 offset:11264
	s_waitcnt lgkmcnt(10)
	v_mfma_f32_16x16x32_bf16 v[2:5], v[224:227], v[240:243], v[2:5]
	s_waitcnt lgkmcnt(9)
	v_mfma_f32_16x16x32_bf16 v[6:9], v[224:227], v[244:247], v[6:9]
	s_waitcnt lgkmcnt(8)
	v_mfma_f32_16x16x32_bf16 v[10:13], v[224:227], v[248:251], v[10:13]
	s_waitcnt lgkmcnt(7)
	v_mfma_f32_16x16x32_bf16 v[14:17], v[224:227], v[156:159], v[14:17]
	s_waitcnt lgkmcnt(6)
	v_mfma_f32_16x16x32_bf16 v[18:21], v[228:231], v[240:243], v[18:21]
	v_mfma_f32_16x16x32_bf16 v[22:25], v[228:231], v[244:247], v[22:25]
	v_mfma_f32_16x16x32_bf16 v[26:29], v[228:231], v[248:251], v[26:29]
	v_mfma_f32_16x16x32_bf16 v[30:33], v[228:231], v[156:159], v[30:33]
	s_waitcnt lgkmcnt(5)
	v_mfma_f32_16x16x32_bf16 v[34:37], v[232:235], v[240:243], v[34:37]
	v_mfma_f32_16x16x32_bf16 v[38:41], v[232:235], v[244:247], v[38:41]
	v_mfma_f32_16x16x32_bf16 v[42:45], v[232:235], v[248:251], v[42:45]
	v_mfma_f32_16x16x32_bf16 v[46:49], v[232:235], v[156:159], v[46:49]
	s_waitcnt lgkmcnt(4)
	v_mfma_f32_16x16x32_bf16 v[50:53], v[236:239], v[240:243], v[50:53]
	v_mfma_f32_16x16x32_bf16 v[54:57], v[236:239], v[244:247], v[54:57]
	v_mfma_f32_16x16x32_bf16 v[58:61], v[236:239], v[248:251], v[58:61]
	v_mfma_f32_16x16x32_bf16 v[62:65], v[236:239], v[156:159], v[62:65]
	s_waitcnt lgkmcnt(3)
	v_mfma_f32_16x16x32_bf16 v[74:77], v[224:227], v[160:163], v[74:77]
	s_waitcnt lgkmcnt(2)
	v_mfma_f32_16x16x32_bf16 v[78:81], v[224:227], v[164:167], v[78:81]
	s_waitcnt lgkmcnt(1)
	v_mfma_f32_16x16x32_bf16 v[82:85], v[224:227], v[168:171], v[82:85]
	s_waitcnt lgkmcnt(0)
	v_mfma_f32_16x16x32_bf16 v[86:89], v[224:227], v[122:125], v[86:89]
	v_mfma_f32_16x16x32_bf16 v[90:93], v[228:231], v[160:163], v[90:93]
	v_mfma_f32_16x16x32_bf16 v[94:97], v[228:231], v[164:167], v[94:97]
	v_mfma_f32_16x16x32_bf16 v[98:101], v[228:231], v[168:171], v[98:101]
	v_mfma_f32_16x16x32_bf16 v[102:105], v[228:231], v[122:125], v[102:105]
	v_mfma_f32_16x16x32_bf16 v[106:109], v[232:235], v[160:163], v[106:109]
	v_mfma_f32_16x16x32_bf16 v[110:113], v[232:235], v[164:167], v[110:113]
	v_mfma_f32_16x16x32_bf16 v[114:117], v[232:235], v[168:171], v[114:117]
	v_mfma_f32_16x16x32_bf16 v[118:121], v[232:235], v[122:125], v[118:121]
	v_mfma_f32_16x16x32_bf16 v[208:211], v[236:239], v[160:163], v[208:211]
	v_mfma_f32_16x16x32_bf16 v[212:215], v[236:239], v[164:167], v[212:215]
	v_mfma_f32_16x16x32_bf16 v[216:219], v[236:239], v[168:171], v[216:219]
	v_mfma_f32_16x16x32_bf16 v[220:223], v[236:239], v[122:125], v[220:223]
	s_waitcnt vmcnt(6)
	s_barrier
	ds_read_b128 v[224:227], v126 offset:24576
	ds_read_b128 v[240:243], v128 offset:24576
	ds_read_b128 v[244:247], v128 offset:25600
	ds_read_b128 v[248:251], v128 offset:26624
	ds_read_b128 v[156:159], v128 offset:27648
	s_add_u32 m0, s46, 0x0
	s_add_u32 s48, s48, 0x40
	s_addc_u32 s49, s49, 0
	global_load_lds_dwordx4 v138, s[48:49]
	global_load_lds_dwordx4 v139, s[48:49] offset:1024
	s_add_u32 m0, s47, 0x0
	s_add_u32 s50, s50, s13
	s_addc_u32 s51, s51, 0
	global_load_lds_dwordx4 v140, s[50:51]
	global_load_lds_dwordx4 v141, s[50:51] offset:1024
	global_load_lds_dwordx4 v142, s[50:51] offset:2048
	global_load_lds_dwordx4 v143, s[50:51] offset:3072
	ds_read_b128 v[228:231], v126 offset:25600
	ds_read_b128 v[232:235], v126 offset:26624
	ds_read_b128 v[236:239], v126 offset:27648
	ds_read_b128 v[160:163], v128 offset:32768
	ds_read_b128 v[164:167], v128 offset:33792
	ds_read_b128 v[168:171], v128 offset:34816
	ds_read_b128 v[122:125], v128 offset:35840
	s_waitcnt lgkmcnt(10)
	v_mfma_f32_16x16x32_bf16 v[2:5], v[224:227], v[240:243], v[2:5]
	s_waitcnt lgkmcnt(9)
	v_mfma_f32_16x16x32_bf16 v[6:9], v[224:227], v[244:247], v[6:9]
	s_waitcnt lgkmcnt(8)
	v_mfma_f32_16x16x32_bf16 v[10:13], v[224:227], v[248:251], v[10:13]
	s_waitcnt lgkmcnt(7)
	v_mfma_f32_16x16x32_bf16 v[14:17], v[224:227], v[156:159], v[14:17]
	s_waitcnt lgkmcnt(6)
	v_mfma_f32_16x16x32_bf16 v[18:21], v[228:231], v[240:243], v[18:21]
	v_mfma_f32_16x16x32_bf16 v[22:25], v[228:231], v[244:247], v[22:25]
	v_mfma_f32_16x16x32_bf16 v[26:29], v[228:231], v[248:251], v[26:29]
	v_mfma_f32_16x16x32_bf16 v[30:33], v[228:231], v[156:159], v[30:33]
	s_waitcnt lgkmcnt(5)
	v_mfma_f32_16x16x32_bf16 v[34:37], v[232:235], v[240:243], v[34:37]
	v_mfma_f32_16x16x32_bf16 v[38:41], v[232:235], v[244:247], v[38:41]
	v_mfma_f32_16x16x32_bf16 v[42:45], v[232:235], v[248:251], v[42:45]
	v_mfma_f32_16x16x32_bf16 v[46:49], v[232:235], v[156:159], v[46:49]
	s_waitcnt lgkmcnt(4)
	v_mfma_f32_16x16x32_bf16 v[50:53], v[236:239], v[240:243], v[50:53]
	v_mfma_f32_16x16x32_bf16 v[54:57], v[236:239], v[244:247], v[54:57]
	v_mfma_f32_16x16x32_bf16 v[58:61], v[236:239], v[248:251], v[58:61]
	v_mfma_f32_16x16x32_bf16 v[62:65], v[236:239], v[156:159], v[62:65]
	s_waitcnt lgkmcnt(3)
	v_mfma_f32_16x16x32_bf16 v[74:77], v[224:227], v[160:163], v[74:77]
	s_waitcnt lgkmcnt(2)
	v_mfma_f32_16x16x32_bf16 v[78:81], v[224:227], v[164:167], v[78:81]
	s_waitcnt lgkmcnt(1)
	v_mfma_f32_16x16x32_bf16 v[82:85], v[224:227], v[168:171], v[82:85]
	s_waitcnt lgkmcnt(0)
	v_mfma_f32_16x16x32_bf16 v[86:89], v[224:227], v[122:125], v[86:89]
	v_mfma_f32_16x16x32_bf16 v[90:93], v[228:231], v[160:163], v[90:93]
	v_mfma_f32_16x16x32_bf16 v[94:97], v[228:231], v[164:167], v[94:97]
	v_mfma_f32_16x16x32_bf16 v[98:101], v[228:231], v[168:171], v[98:101]
	v_mfma_f32_16x16x32_bf16 v[102:105], v[228:231], v[122:125], v[102:105]
	v_mfma_f32_16x16x32_bf16 v[106:109], v[232:235], v[160:163], v[106:109]
	v_mfma_f32_16x16x32_bf16 v[110:113], v[232:235], v[164:167], v[110:113]
	v_mfma_f32_16x16x32_bf16 v[114:117], v[232:235], v[168:171], v[114:117]
	v_mfma_f32_16x16x32_bf16 v[118:121], v[232:235], v[122:125], v[118:121]
	v_mfma_f32_16x16x32_bf16 v[208:211], v[236:239], v[160:163], v[208:211]
	v_mfma_f32_16x16x32_bf16 v[212:215], v[236:239], v[164:167], v[212:215]
	v_mfma_f32_16x16x32_bf16 v[216:219], v[236:239], v[168:171], v[216:219]
	v_mfma_f32_16x16x32_bf16 v[220:223], v[236:239], v[122:125], v[220:223]
	s_waitcnt vmcnt(6)
	s_barrier
; #define BLOAD(A_, B_, kt) do { _Pragma("unroll") for (int i = 0; i < 4; ++i) { \
;     A_[i] = *(const u32x4*)((const char*)Ap + (aoff + (unsigned)(32 * i * lda + (kt) * 64) * 2u)); B_[i] = *(const u32x4*)((const char*)Wt + (woff + (unsigned)(32 * i * K + (kt) * 64) * 2u)); } } while (0)
; #define BLOAD(A_, B_, kt) do { _Pragma("unroll") for (int i = 0; i < 4; ++i) { \
;     A_[i] = *(const u32x4*)((const char*)Ap + (aoff + (unsigned)(32 * i * lda + (kt) * 64) * 2u)); B_[i] = *(const u32x4*)((const char*)Wt + (woff + (unsigned)(32 * i * K + (kt) * 64) * 2u)); } } while (0)
; #define BSTORE(A_, B_, buf) do { _Pragma("unroll") for (int i = 0; i < 4; ++i) { \
;     *(u32x4*)&As[(buf) * GBUF + (srow + 32 * i) * LDT + sc8] = A_[i]; \
;     *(u32x4*)&Bs[(buf) * GBUF + (srow + 32 * i) * LDT + sc8] = B_[i]; } } while (0)
; template <int NK>
; DI void gemm_run(PF& pf, const u16* __restrict__ Ap, int lda, const u16* __restrict__ Wt, f32x16 (&acc)[2][2], char* smem) {
;     ...
;   __builtin_amdgcn_s_setprio(0);
;   __syncthreads();
;   BSTORE(pf.a0, pf.b0, 0);
;   BLOAD(pf.a0, pf.b0, 2);
;   __syncthreads();
; #pragma unroll
;   for (int kt = 0; kt < nk; kt += 2) {
;     BCOMP(0);
;     BSTORE(pf.a1, pf.b1, 1);
;     if (kt + 3 < nk) BLOAD(pf.a1, pf.b1, kt + 3);
;     __syncthreads();
;     BCOMP(1);
;     if (kt + 2 < nk) { BSTORE(pf.a0, pf.b0, 0); if (kt + 4 < nk) BLOAD(pf.a0, pf.b0, kt + 4); }
;     __syncthreads();
;   }
	ds_read_b128 v[224:227], v126 offset:49152
	ds_read_b128 v[240:243], v128 offset:49152
	ds_read_b128 v[244:247], v128 offset:50176
	ds_read_b128 v[248:251], v128 offset:51200
	ds_read_b128 v[156:159], v128 offset:52224
	s_add_u32 m0, s46, 0x6000
	s_add_u32 s48, s48, 0x40
	s_addc_u32 s49, s49, 0
	global_load_lds_dwordx4 v138, s[48:49]
	global_load_lds_dwordx4 v139, s[48:49] offset:1024
	s_add_u32 m0, s47, 0x6000
	s_add_u32 s50, s50, s13
	s_addc_u32 s51, s51, 0
	global_load_lds_dwordx4 v140, s[50:51]
	global_load_lds_dwordx4 v141, s[50:51] offset:1024
	global_load_lds_dwordx4 v142, s[50:51] offset:2048
	global_load_lds_dwordx4 v143, s[50:51] offset:3072
	ds_read_b128 v[228:231], v126 offset:50176
	ds_read_b128 v[232:235], v126 offset:51200
	ds_read_b128 v[236:239], v126 offset:52224
	ds_read_b128 v[160:163], v128 offset:57344
	ds_read_b128 v[164:167], v128 offset:58368
	ds_read_b128 v[168:171], v128 offset:59392
	ds_read_b128 v[122:125], v128 offset:60416
	s_waitcnt lgkmcnt(10)
	v_mfma_f32_16x16x32_bf16 v[2:5], v[224:227], v[240:243], v[2:5]
	s_waitcnt lgkmcnt(9)
	v_mfma_f32_16x16x32_bf16 v[6:9], v[224:227], v[244:247], v[6:9]
	s_waitcnt lgkmcnt(8)
	v_mfma_f32_16x16x32_bf16 v[10:13], v[224:227], v[248:251], v[10:13]
	s_waitcnt lgkmcnt(7)
	v_mfma_f32_16x16x32_bf16 v[14:17], v[224:227], v[156:159], v[14:17]
	s_waitcnt lgkmcnt(6)
	v_mfma_f32_16x16x32_bf16 v[18:21], v[228:231], v[240:243], v[18:21]
	v_mfma_f32_16x16x32_bf16 v[22:25], v[228:231], v[244:247], v[22:25]
	v_mfma_f32_16x16x32_bf16 v[26:29], v[228:231], v[248:251], v[26:29]
	v_mfma_f32_16x16x32_bf16 v[30:33], v[228:231], v[156:159], v[30:33]
	s_waitcnt lgkmcnt(5)
	v_mfma_f32_16x16x32_bf16 v[34:37], v[232:235], v[240:243], v[34:37]
	v_mfma_f32_16x16x32_bf16 v[38:41], v[232:235], v[244:247], v[38:41]
	v_mfma_f32_16x16x32_bf16 v[42:45], v[232:235], v[248:251], v[42:45]
	v_mfma_f32_16x16x32_bf16 v[46:49], v[232:235], v[156:159], v[46:49]
	s_waitcnt lgkmcnt(4)
	v_mfma_f32_16x16x32_bf16 v[50:53], v[236:239], v[240:243], v[50:53]
	v_mfma_f32_16x16x32_bf16 v[54:57], v[236:239], v[244:247], v[54:57]
	v_mfma_f32_16x16x32_bf16 v[58:61], v[236:239], v[248:251], v[58:61]
	v_mfma_f32_16x16x32_bf16 v[62:65], v[236:239], v[156:159], v[62:65]
	s_waitcnt lgkmcnt(3)
	v_mfma_f32_16x16x32_bf16 v[74:77], v[224:227], v[160:163], v[74:77]
	s_waitcnt lgkmcnt(2)
	v_mfma_f32_16x16x32_bf16 v[78:81], v[224:227], v[164:167], v[78:81]
	s_waitcnt lgkmcnt(1)
	v_mfma_f32_16x16x32_bf16 v[82:85], v[224:227], v[168:171], v[82:85]
	s_waitcnt lgkmcnt(0)
	v_mfma_f32_16x16x32_bf16 v[86:89], v[224:227], v[122:125], v[86:89]
	v_mfma_f32_16x16x32_bf16 v[90:93], v[228:231], v[160:163], v[90:93]
	v_mfma_f32_16x16x32_bf16 v[94:97], v[228:231], v[164:167], v[94:97]
	v_mfma_f32_16x16x32_bf16 v[98:101], v[228:231], v[168:171], v[98:101]
	v_mfma_f32_16x16x32_bf16 v[102:105], v[228:231], v[122:125], v[102:105]
	v_mfma_f32_16x16x32_bf16 v[106:109], v[232:235], v[160:163], v[106:109]
	v_mfma_f32_16x16x32_bf16 v[110:113], v[232:235], v[164:167], v[110:113]
	v_mfma_f32_16x16x32_bf16 v[114:117], v[232:235], v[168:171], v[114:117]
	v_mfma_f32_16x16x32_bf16 v[118:121], v[232:235], v[122:125], v[118:121]
	v_mfma_f32_16x16x32_bf16 v[208:211], v[236:239], v[160:163], v[208:211]
	v_mfma_f32_16x16x32_bf16 v[212:215], v[236:239], v[164:167], v[212:215]
	v_mfma_f32_16x16x32_bf16 v[216:219], v[236:239], v[168:171], v[216:219]
	v_mfma_f32_16x16x32_bf16 v[220:223], v[236:239], v[122:125], v[220:223]
	s_sub_u32 s12, s12, 1
	s_cmp_lg_u32 s12, 0
	s_cbranch_scc1 .Linp_kloop
	s_waitcnt vmcnt(6)
	s_barrier
; #define BLOAD(A_, B_, kt) do { _Pragma("unroll") for (int i = 0; i < 4; ++i) { \
;     A_[i] = *(const u32x4*)((const char*)Ap + (aoff + (unsigned)(32 * i * lda + (kt) * 64) * 2u)); B_[i] = *(const u32x4*)((const char*)Wt + (woff + (unsigned)(32 * i * K + (kt) * 64) * 2u)); } } while (0)
; #define BLOAD(A_, B_, kt) do { _Pragma("unroll") for (int i = 0; i < 4; ++i) { \
;     A_[i] = *(const u32x4*)((const char*)Ap + (aoff + (unsigned)(32 * i * lda + (kt) * 64) * 2u)); B_[i] = *(const u32x4*)((const char*)Wt + (woff + (unsigned)(32 * i * K + (kt) * 64) * 2u)); } } while (0)
; #define BSTORE(A_, B_, buf) do { _Pragma("unroll") for (int i = 0; i < 4; ++i) { \
;     *(u32x4*)&As[(buf) * GBUF + (srow + 32 * i) * LDT + sc8] = A_[i]; \
;     *(u32x4*)&Bs[(buf) * GBUF + (srow + 32 * i) * LDT + sc8] = B_[i]; } } while (0)
; template <int NK>
; DI void gemm_run(PF& pf, const u16* __restrict__ Ap, int lda, const u16* __restrict__ Wt, f32x16 (&acc)[2][2], char* smem) {
;     ...
; #pragma unroll
;   for (int kt = 0; kt < nk; kt += 2) {
;     BCOMP(0);
;     BSTORE(pf.a1, pf.b1, 1);
;     if (kt + 3 < nk) BLOAD(pf.a1, pf.b1, kt + 3);
;     __syncthreads();
;     BCOMP(1);
;     if (kt + 2 < nk) { BSTORE(pf.a0, pf.b0, 0); if (kt + 4 < nk) BLOAD(pf.a0, pf.b0, kt + 4); }
;     __syncthreads();
;   }
	ds_read_b128 v[224:227], v126 offset:0
	ds_read_b128 v[240:243], v128 offset:0
	ds_read_b128 v[244:247], v128 offset:1024
	ds_read_b128 v[248:251], v128 offset:2048
	ds_read_b128 v[156:159], v128 offset:3072
	ds_read_b128 v[228:231], v126 offset:1024
	ds_read_b128 v[232:235], v126 offset:2048
	ds_read_b128 v[236:239], v126 offset:3072
	ds_read_b128 v[160:163], v128 offset:8192
	ds_read_b128 v[164:167], v128 offset:9216
	ds_read_b128 v[168:171], v128 offset:10240
	ds_read_b128 v[122:125], v128 offset:11264
	s_waitcnt lgkmcnt(10)
	v_mfma_f32_16x16x32_bf16 v[2:5], v[224:227], v[240:243], v[2:5]
	s_waitcnt lgkmcnt(9)
	v_mfma_f32_16x16x32_bf16 v[6:9], v[224:227], v[244:247], v[6:9]
	s_waitcnt lgkmcnt(8)
	v_mfma_f32_16x16x32_bf16 v[10:13], v[224:227], v[248:251], v[10:13]
	s_waitcnt lgkmcnt(7)
	v_mfma_f32_16x16x32_bf16 v[14:17], v[224:227], v[156:159], v[14:17]
	s_waitcnt lgkmcnt(6)
	v_mfma_f32_16x16x32_bf16 v[18:21], v[228:231], v[240:243], v[18:21]
	v_mfma_f32_16x16x32_bf16 v[22:25], v[228:231], v[244:247], v[22:25]
	v_mfma_f32_16x16x32_bf16 v[26:29], v[228:231], v[248:251], v[26:29]
	v_mfma_f32_16x16x32_bf16 v[30:33], v[228:231], v[156:159], v[30:33]
	s_waitcnt lgkmcnt(5)
	v_mfma_f32_16x16x32_bf16 v[34:37], v[232:235], v[240:243], v[34:37]
	v_mfma_f32_16x16x32_bf16 v[38:41], v[232:235], v[244:247], v[38:41]
	v_mfma_f32_16x16x32_bf16 v[42:45], v[232:235], v[248:251], v[42:45]
	v_mfma_f32_16x16x32_bf16 v[46:49], v[232:235], v[156:159], v[46:49]
	s_waitcnt lgkmcnt(4)
	v_mfma_f32_16x16x32_bf16 v[50:53], v[236:239], v[240:243], v[50:53]
	v_mfma_f32_16x16x32_bf16 v[54:57], v[236:239], v[244:247], v[54:57]
	v_mfma_f32_16x16x32_bf16 v[58:61], v[236:239], v[248:251], v[58:61]
	v_mfma_f32_16x16x32_bf16 v[62:65], v[236:239], v[156:159], v[62:65]
	s_waitcnt lgkmcnt(3)
	v_mfma_f32_16x16x32_bf16 v[74:77], v[224:227], v[160:163], v[74:77]
	s_waitcnt lgkmcnt(2)
	v_mfma_f32_16x16x32_bf16 v[78:81], v[224:227], v[164:167], v[78:81]
	s_waitcnt lgkmcnt(1)
	v_mfma_f32_16x16x32_bf16 v[82:85], v[224:227], v[168:171], v[82:85]
	s_waitcnt lgkmcnt(0)
	v_mfma_f32_16x16x32_bf16 v[86:89], v[224:227], v[122:125], v[86:89]
	v_mfma_f32_16x16x32_bf16 v[90:93], v[228:231], v[160:163], v[90:93]
	v_mfma_f32_16x16x32_bf16 v[94:97], v[228:231], v[164:167], v[94:97]
	v_mfma_f32_16x16x32_bf16 v[98:101], v[228:231], v[168:171], v[98:101]
	v_mfma_f32_16x16x32_bf16 v[102:105], v[228:231], v[122:125], v[102:105]
	v_mfma_f32_16x16x32_bf16 v[106:109], v[232:235], v[160:163], v[106:109]
	v_mfma_f32_16x16x32_bf16 v[110:113], v[232:235], v[164:167], v[110:113]
	v_mfma_f32_16x16x32_bf16 v[114:117], v[232:235], v[168:171], v[114:117]
	v_mfma_f32_16x16x32_bf16 v[118:121], v[232:235], v[122:125], v[118:121]
	v_mfma_f32_16x16x32_bf16 v[208:211], v[236:239], v[160:163], v[208:211]
	v_mfma_f32_16x16x32_bf16 v[212:215], v[236:239], v[164:167], v[212:215]
	v_mfma_f32_16x16x32_bf16 v[216:219], v[236:239], v[168:171], v[216:219]
	v_mfma_f32_16x16x32_bf16 v[220:223], v[236:239], v[122:125], v[220:223]
	s_waitcnt vmcnt(0)
	s_barrier
	ds_read_b128 v[224:227], v126 offset:24576
	ds_read_b128 v[240:243], v128 offset:24576
	ds_read_b128 v[244:247], v128 offset:25600
	ds_read_b128 v[248:251], v128 offset:26624
	ds_read_b128 v[156:159], v128 offset:27648
	ds_read_b128 v[228:231], v126 offset:25600
	ds_read_b128 v[232:235], v126 offset:26624
	ds_read_b128 v[236:239], v126 offset:27648
	ds_read_b128 v[160:163], v128 offset:32768
	ds_read_b128 v[164:167], v128 offset:33792
	ds_read_b128 v[168:171], v128 offset:34816
	ds_read_b128 v[122:125], v128 offset:35840
	s_waitcnt lgkmcnt(10)
	v_mfma_f32_16x16x32_bf16 v[2:5], v[224:227], v[240:243], v[2:5]
	s_waitcnt lgkmcnt(9)
	v_mfma_f32_16x16x32_bf16 v[6:9], v[224:227], v[244:247], v[6:9]
	s_waitcnt lgkmcnt(8)
	v_mfma_f32_16x16x32_bf16 v[10:13], v[224:227], v[248:251], v[10:13]
	s_waitcnt lgkmcnt(7)
	v_mfma_f32_16x16x32_bf16 v[14:17], v[224:227], v[156:159], v[14:17]
	s_waitcnt lgkmcnt(6)
	v_mfma_f32_16x16x32_bf16 v[18:21], v[228:231], v[240:243], v[18:21]
	v_mfma_f32_16x16x32_bf16 v[22:25], v[228:231], v[244:247], v[22:25]
	v_mfma_f32_16x16x32_bf16 v[26:29], v[228:231], v[248:251], v[26:29]
	v_mfma_f32_16x16x32_bf16 v[30:33], v[228:231], v[156:159], v[30:33]
	s_waitcnt lgkmcnt(5)
	v_mfma_f32_16x16x32_bf16 v[34:37], v[232:235], v[240:243], v[34:37]
	v_mfma_f32_16x16x32_bf16 v[38:41], v[232:235], v[244:247], v[38:41]
	v_mfma_f32_16x16x32_bf16 v[42:45], v[232:235], v[248:251], v[42:45]
	v_mfma_f32_16x16x32_bf16 v[46:49], v[232:235], v[156:159], v[46:49]
	s_waitcnt lgkmcnt(4)
	v_mfma_f32_16x16x32_bf16 v[50:53], v[236:239], v[240:243], v[50:53]
	v_mfma_f32_16x16x32_bf16 v[54:57], v[236:239], v[244:247], v[54:57]
	v_mfma_f32_16x16x32_bf16 v[58:61], v[236:239], v[248:251], v[58:61]
	v_mfma_f32_16x16x32_bf16 v[62:65], v[236:239], v[156:159], v[62:65]
	s_waitcnt lgkmcnt(3)
	v_mfma_f32_16x16x32_bf16 v[74:77], v[224:227], v[160:163], v[74:77]
	s_waitcnt lgkmcnt(2)
	v_mfma_f32_16x16x32_bf16 v[78:81], v[224:227], v[164:167], v[78:81]
	s_waitcnt lgkmcnt(1)
	v_mfma_f32_16x16x32_bf16 v[82:85], v[224:227], v[168:171], v[82:85]
	s_waitcnt lgkmcnt(0)
	v_mfma_f32_16x16x32_bf16 v[86:89], v[224:227], v[122:125], v[86:89]
	v_mfma_f32_16x16x32_bf16 v[90:93], v[228:231], v[160:163], v[90:93]
	v_mfma_f32_16x16x32_bf16 v[94:97], v[228:231], v[164:167], v[94:97]
	v_mfma_f32_16x16x32_bf16 v[98:101], v[228:231], v[168:171], v[98:101]
	v_mfma_f32_16x16x32_bf16 v[102:105], v[228:231], v[122:125], v[102:105]
	v_mfma_f32_16x16x32_bf16 v[106:109], v[232:235], v[160:163], v[106:109]
	v_mfma_f32_16x16x32_bf16 v[110:113], v[232:235], v[164:167], v[110:113]
	v_mfma_f32_16x16x32_bf16 v[114:117], v[232:235], v[168:171], v[114:117]
	v_mfma_f32_16x16x32_bf16 v[118:121], v[232:235], v[122:125], v[118:121]
	v_mfma_f32_16x16x32_bf16 v[208:211], v[236:239], v[160:163], v[208:211]
	v_mfma_f32_16x16x32_bf16 v[212:215], v[236:239], v[164:167], v[212:215]
	v_mfma_f32_16x16x32_bf16 v[216:219], v[236:239], v[168:171], v[216:219]
	v_mfma_f32_16x16x32_bf16 v[220:223], v[236:239], v[122:125], v[220:223]
	s_barrier
	s_branch .Linp_post
